# G2 mid hook paired gate reads (dwordx4 + v_permlane16_swap) with per-group counted waits so the gate math overlaps the later loads
# speedup vs baseline: 1.0105x; 1.0057x over previous
.LBB0_1080:
	s_andn2_b64 vcc, exec, s[26:27]
	s_cbranch_vccnz .LBB0_1082
	v_mov_b32_e32 v0, v151
	s_movk_i32 s30, 0x1320
	s_nop 0
	v_mad_u64_u32 v[2:3], s[28:29], v0, s30, v[136:137]
	v_mov_b32_e32 v231, 0
	v_bfe_u32 v232, v186, 4, 1
	v_mul_u32_u24_e32 v232, 0x131fc, v232
	v_add_u32_e32 v2, v2, v232
	v_add_u32_e32 v230, s13, v2
	v_lshlrev_b64 v[232:233], 1, v[230:231]
	v_lshl_add_u64 v[198:199], s[4:5], 0, v[232:233]
	v_lshl_add_u64 v[202:203], s[8:9], 0, v[232:233]
	global_load_dwordx4 v[198:201], v[198:199], off
	global_load_dwordx4 v[202:205], v[202:203], off
	v_add_u32_e32 v230, s56, v2
	v_lshlrev_b64 v[232:233], 1, v[230:231]
	v_lshl_add_u64 v[206:207], s[4:5], 0, v[232:233]
	v_lshl_add_u64 v[210:211], s[8:9], 0, v[232:233]
	global_load_dwordx4 v[206:209], v[206:207], off
	global_load_dwordx4 v[210:213], v[210:211], off
	v_add_u32_e32 v230, s57, v2
	v_lshlrev_b64 v[232:233], 1, v[230:231]
	v_lshl_add_u64 v[214:215], s[4:5], 0, v[232:233]
	v_lshl_add_u64 v[218:219], s[8:9], 0, v[232:233]
	global_load_dwordx4 v[214:217], v[214:215], off
	global_load_dwordx4 v[218:221], v[218:219], off
	v_add_u32_e32 v230, s58, v2
	v_lshlrev_b64 v[232:233], 1, v[230:231]
	v_lshl_add_u64 v[222:223], s[4:5], 0, v[232:233]
	v_lshl_add_u64 v[226:227], s[8:9], 0, v[232:233]
	global_load_dwordx4 v[222:225], v[222:223], off
	global_load_dwordx4 v[226:229], v[226:227], off
	s_waitcnt vmcnt(6)
	v_permlane16_swap_b32_e32 v198, v200
	v_permlane16_swap_b32_e32 v199, v201
	v_permlane16_swap_b32_e32 v202, v204
	v_permlane16_swap_b32_e32 v203, v205
	v_lshlrev_b32_e32 v0, 16, v202
	v_mul_f32_e32 v0, 0xbfb8aa3b, v0
	v_exp_f32_e32 v0, v0
	s_nop 0
	v_min_f32_e32 v168, 0x7149f2ca, v0
	v_lshlrev_b32_e32 v0, 16, v198
	v_mul_f32_e32 v0, 0xbfb8aa3b, v0
	v_exp_f32_e32 v0, v0
	s_nop 0
	v_min_f32_e32 v0, 0x7149f2ca, v0
	v_add_f32_e32 v0, 1.0, v0
	v_rcp_f32_e32 v170, v0
	v_and_b32_e32 v0, 0xffff0000, v202
	v_mul_f32_e32 v0, 0xbfb8aa3b, v0
	v_exp_f32_e32 v0, v0
	s_nop 0
	v_min_f32_e32 v169, 0x7149f2ca, v0
	v_and_b32_e32 v0, 0xffff0000, v198
	v_mul_f32_e32 v0, 0xbfb8aa3b, v0
	v_exp_f32_e32 v0, v0
	v_add_f32_e32 v168, 1.0, v168
	v_add_f32_e32 v169, 1.0, v169
	v_min_f32_e32 v0, 0x7149f2ca, v0
	v_add_f32_e32 v0, 1.0, v0
	v_rcp_f32_e32 v171, v0
	v_lshlrev_b32_e32 v0, 16, v203
	v_mul_f32_e32 v0, 0xbfb8aa3b, v0
	v_exp_f32_e32 v0, v0
	v_mul_f32_e32 v168, v168, v170
	v_mul_f32_e32 v169, v169, v171
	v_min_f32_e32 v146, 0x7149f2ca, v0
	v_lshlrev_b32_e32 v0, 16, v199
	v_mul_f32_e32 v0, 0xbfb8aa3b, v0
	v_exp_f32_e32 v0, v0
	v_mul_f32_e32 v128, v128, v168
	v_mul_f32_e32 v129, v129, v169
	v_min_f32_e32 v0, 0x7149f2ca, v0
	v_add_f32_e32 v0, 1.0, v0
	v_rcp_f32_e32 v166, v0
	v_and_b32_e32 v0, 0xffff0000, v203
	v_mul_f32_e32 v0, 0xbfb8aa3b, v0
	v_exp_f32_e32 v0, v0
	s_nop 0
	v_min_f32_e32 v147, 0x7149f2ca, v0
	v_and_b32_e32 v0, 0xffff0000, v199
	v_mul_f32_e32 v0, 0xbfb8aa3b, v0
	v_exp_f32_e32 v0, v0
	v_add_f32_e32 v146, 1.0, v146
	v_add_f32_e32 v147, 1.0, v147
	v_min_f32_e32 v0, 0x7149f2ca, v0
	v_add_f32_e32 v0, 1.0, v0
	v_rcp_f32_e32 v167, v0
	s_nop 0
	v_mul_f32_e32 v146, v146, v166
	v_mul_f32_e32 v147, v147, v167
	s_nop 0
	v_mul_f32_e32 v130, v130, v146
	v_mul_f32_e32 v131, v131, v147
	s_nop 0
	s_nop 0
	s_nop 0
	s_waitcnt vmcnt(4)
	v_permlane16_swap_b32_e32 v206, v208
	v_permlane16_swap_b32_e32 v207, v209
	v_permlane16_swap_b32_e32 v210, v212
	v_permlane16_swap_b32_e32 v211, v213
	v_lshlrev_b32_e32 v0, 16, v210
	v_mul_f32_e32 v0, 0xbfb8aa3b, v0
	v_exp_f32_e32 v0, v0
	s_nop 0
	v_min_f32_e32 v168, 0x7149f2ca, v0
	v_lshlrev_b32_e32 v0, 16, v206
	v_mul_f32_e32 v0, 0xbfb8aa3b, v0
	v_exp_f32_e32 v0, v0
	s_nop 0
	v_min_f32_e32 v0, 0x7149f2ca, v0
	v_add_f32_e32 v0, 1.0, v0
	v_rcp_f32_e32 v170, v0
	v_and_b32_e32 v0, 0xffff0000, v210
	v_mul_f32_e32 v0, 0xbfb8aa3b, v0
	v_exp_f32_e32 v0, v0
	s_nop 0
	v_min_f32_e32 v169, 0x7149f2ca, v0
	v_and_b32_e32 v0, 0xffff0000, v206
	v_mul_f32_e32 v0, 0xbfb8aa3b, v0
	v_exp_f32_e32 v0, v0
	v_add_f32_e32 v168, 1.0, v168
	v_add_f32_e32 v169, 1.0, v169
	v_min_f32_e32 v0, 0x7149f2ca, v0
	v_add_f32_e32 v0, 1.0, v0
	v_rcp_f32_e32 v171, v0
	v_lshlrev_b32_e32 v0, 16, v211
	v_mul_f32_e32 v0, 0xbfb8aa3b, v0
	v_exp_f32_e32 v0, v0
	v_mul_f32_e32 v168, v168, v170
	v_mul_f32_e32 v169, v169, v171
	v_min_f32_e32 v146, 0x7149f2ca, v0
	v_lshlrev_b32_e32 v0, 16, v207
	v_mul_f32_e32 v0, 0xbfb8aa3b, v0
	v_exp_f32_e32 v0, v0
	v_mul_f32_e32 v124, v124, v168
	v_mul_f32_e32 v125, v125, v169
	v_min_f32_e32 v0, 0x7149f2ca, v0
	v_add_f32_e32 v0, 1.0, v0
	v_rcp_f32_e32 v166, v0
	v_and_b32_e32 v0, 0xffff0000, v211
	v_mul_f32_e32 v0, 0xbfb8aa3b, v0
	v_exp_f32_e32 v0, v0
	s_nop 0
	v_min_f32_e32 v147, 0x7149f2ca, v0
	v_and_b32_e32 v0, 0xffff0000, v207
	v_mul_f32_e32 v0, 0xbfb8aa3b, v0
	v_exp_f32_e32 v0, v0
	v_add_f32_e32 v146, 1.0, v146
	v_add_f32_e32 v147, 1.0, v147
	v_min_f32_e32 v0, 0x7149f2ca, v0
	v_add_f32_e32 v0, 1.0, v0
	v_rcp_f32_e32 v167, v0
	s_nop 0
	v_mul_f32_e32 v146, v146, v166
	v_mul_f32_e32 v147, v147, v167
	s_nop 0
	v_mul_f32_e32 v126, v126, v146
	v_mul_f32_e32 v127, v127, v147
	s_nop 0
	s_nop 0
	s_nop 0
	s_waitcnt vmcnt(2)
	v_permlane16_swap_b32_e32 v214, v216
	v_permlane16_swap_b32_e32 v215, v217
	v_permlane16_swap_b32_e32 v218, v220
	v_permlane16_swap_b32_e32 v219, v221
	v_lshlrev_b32_e32 v0, 16, v218
	v_mul_f32_e32 v0, 0xbfb8aa3b, v0
	v_exp_f32_e32 v0, v0
	s_nop 0
	v_min_f32_e32 v168, 0x7149f2ca, v0
	v_lshlrev_b32_e32 v0, 16, v214
	v_mul_f32_e32 v0, 0xbfb8aa3b, v0
	v_exp_f32_e32 v0, v0
	s_nop 0
	v_min_f32_e32 v0, 0x7149f2ca, v0
	v_add_f32_e32 v0, 1.0, v0
	v_rcp_f32_e32 v170, v0
	v_and_b32_e32 v0, 0xffff0000, v218
	v_mul_f32_e32 v0, 0xbfb8aa3b, v0
	v_exp_f32_e32 v0, v0
	s_nop 0
	v_min_f32_e32 v169, 0x7149f2ca, v0
	v_and_b32_e32 v0, 0xffff0000, v214
	v_mul_f32_e32 v0, 0xbfb8aa3b, v0
	v_exp_f32_e32 v0, v0
	v_add_f32_e32 v168, 1.0, v168
	v_add_f32_e32 v169, 1.0, v169
	v_min_f32_e32 v0, 0x7149f2ca, v0
	v_add_f32_e32 v0, 1.0, v0
	v_rcp_f32_e32 v171, v0
	v_lshlrev_b32_e32 v0, 16, v219
	v_mul_f32_e32 v0, 0xbfb8aa3b, v0
	v_exp_f32_e32 v0, v0
	v_mul_f32_e32 v168, v168, v170
	v_mul_f32_e32 v169, v169, v171
	v_min_f32_e32 v146, 0x7149f2ca, v0
	v_lshlrev_b32_e32 v0, 16, v215
	v_mul_f32_e32 v0, 0xbfb8aa3b, v0
	v_exp_f32_e32 v0, v0
	v_mul_f32_e32 v120, v120, v168
	v_mul_f32_e32 v121, v121, v169
	v_min_f32_e32 v0, 0x7149f2ca, v0
	v_add_f32_e32 v0, 1.0, v0
	v_rcp_f32_e32 v166, v0
	v_and_b32_e32 v0, 0xffff0000, v219
	v_mul_f32_e32 v0, 0xbfb8aa3b, v0
	v_exp_f32_e32 v0, v0
	s_nop 0
	v_min_f32_e32 v147, 0x7149f2ca, v0
	v_and_b32_e32 v0, 0xffff0000, v215
	v_mul_f32_e32 v0, 0xbfb8aa3b, v0
	v_exp_f32_e32 v0, v0
	v_add_f32_e32 v146, 1.0, v146
	v_add_f32_e32 v147, 1.0, v147
	v_min_f32_e32 v0, 0x7149f2ca, v0
	v_add_f32_e32 v0, 1.0, v0
	v_rcp_f32_e32 v167, v0
	s_nop 0
	s_nop 0
	v_mul_f32_e32 v146, v146, v166
	v_mul_f32_e32 v147, v147, v167
	s_nop 0
	v_mul_f32_e32 v122, v122, v146
	v_mul_f32_e32 v123, v123, v147
	s_nop 0
	s_nop 0
	s_waitcnt vmcnt(0)
	v_permlane16_swap_b32_e32 v222, v224
	v_permlane16_swap_b32_e32 v223, v225
	v_permlane16_swap_b32_e32 v226, v228
	v_permlane16_swap_b32_e32 v227, v229
	v_lshlrev_b32_e32 v0, 16, v226
	v_mul_f32_e32 v0, 0xbfb8aa3b, v0
	v_exp_f32_e32 v0, v0
	s_nop 0
	v_min_f32_e32 v166, 0x7149f2ca, v0
	v_lshlrev_b32_e32 v0, 16, v222
	v_mul_f32_e32 v0, 0xbfb8aa3b, v0
	v_exp_f32_e32 v0, v0
	s_nop 0
	v_min_f32_e32 v0, 0x7149f2ca, v0
	v_add_f32_e32 v0, 1.0, v0
	v_rcp_f32_e32 v168, v0
	v_and_b32_e32 v0, 0xffff0000, v226
	v_mul_f32_e32 v0, 0xbfb8aa3b, v0
	v_exp_f32_e32 v0, v0
	s_nop 0
	v_min_f32_e32 v167, 0x7149f2ca, v0
	v_and_b32_e32 v0, 0xffff0000, v222
	v_mul_f32_e32 v0, 0xbfb8aa3b, v0
	v_exp_f32_e32 v0, v0
	v_add_f32_e32 v166, 1.0, v166
	v_add_f32_e32 v167, 1.0, v167
	v_min_f32_e32 v0, 0x7149f2ca, v0
	v_add_f32_e32 v0, 1.0, v0
	v_rcp_f32_e32 v169, v0
	v_lshlrev_b32_e32 v0, 16, v227
	v_mul_f32_e32 v0, 0xbfb8aa3b, v0
	v_exp_f32_e32 v0, v0
	v_mul_f32_e32 v166, v166, v168
	v_mul_f32_e32 v167, v167, v169
	v_min_f32_e32 v2, 0x7149f2ca, v0
	v_lshlrev_b32_e32 v0, 16, v223
	v_mul_f32_e32 v0, 0xbfb8aa3b, v0
	v_exp_f32_e32 v0, v0
	v_mul_f32_e32 v116, v116, v166
	v_mul_f32_e32 v117, v117, v167
	v_min_f32_e32 v0, 0x7149f2ca, v0
	v_add_f32_e32 v0, 1.0, v0
	v_rcp_f32_e32 v146, v0
	v_and_b32_e32 v0, 0xffff0000, v227
	v_mul_f32_e32 v0, 0xbfb8aa3b, v0
	v_exp_f32_e32 v0, v0
	s_nop 0
	v_min_f32_e32 v3, 0x7149f2ca, v0
	v_and_b32_e32 v0, 0xffff0000, v223
	v_mul_f32_e32 v0, 0xbfb8aa3b, v0
	v_exp_f32_e32 v0, v0
	v_add_f32_e32 v2, 1.0, v2
	v_add_f32_e32 v3, 1.0, v3
	v_min_f32_e32 v0, 0x7149f2ca, v0
	v_add_f32_e32 v0, 1.0, v0
	v_rcp_f32_e32 v147, v0
	v_mov_b32_e32 v0, v152
	v_mul_f32_e32 v2, v2, v146
	v_mul_f32_e32 v3, v3, v147
	s_nop 0
	v_mul_f32_e32 v118, v118, v2
	v_mul_f32_e32 v119, v119, v3
	s_nop 0
	s_nop 0
	v_mad_u64_u32 v[2:3], s[28:29], v0, s30, v[136:137]
	v_lshlrev_b32_e32 v0, 16, v204
	v_mul_f32_e32 v0, 0xbfb8aa3b, v0
	v_exp_f32_e32 v0, v0
	s_nop 0
	v_min_f32_e32 v168, 0x7149f2ca, v0
	v_lshlrev_b32_e32 v0, 16, v200
	v_mul_f32_e32 v0, 0xbfb8aa3b, v0
	v_exp_f32_e32 v0, v0
	s_nop 0
	v_min_f32_e32 v0, 0x7149f2ca, v0
	v_add_f32_e32 v0, 1.0, v0
	v_rcp_f32_e32 v170, v0
	v_and_b32_e32 v0, 0xffff0000, v204
	v_mul_f32_e32 v0, 0xbfb8aa3b, v0
	v_exp_f32_e32 v0, v0
	s_nop 0
	v_min_f32_e32 v169, 0x7149f2ca, v0
	v_and_b32_e32 v0, 0xffff0000, v200
	v_mul_f32_e32 v0, 0xbfb8aa3b, v0
	v_exp_f32_e32 v0, v0
	v_add_f32_e32 v168, 1.0, v168
	v_add_f32_e32 v169, 1.0, v169
	v_min_f32_e32 v0, 0x7149f2ca, v0
	v_add_f32_e32 v0, 1.0, v0
	v_rcp_f32_e32 v171, v0
	v_lshlrev_b32_e32 v0, 16, v205
	v_mul_f32_e32 v0, 0xbfb8aa3b, v0
	v_exp_f32_e32 v0, v0
	v_mul_f32_e32 v168, v168, v170
	v_mul_f32_e32 v169, v169, v171
	v_min_f32_e32 v146, 0x7149f2ca, v0
	v_lshlrev_b32_e32 v0, 16, v201
	v_mul_f32_e32 v0, 0xbfb8aa3b, v0
	v_exp_f32_e32 v0, v0
	v_mul_f32_e32 v112, v112, v168
	v_mul_f32_e32 v113, v113, v169
	v_min_f32_e32 v0, 0x7149f2ca, v0
	v_add_f32_e32 v0, 1.0, v0
	v_rcp_f32_e32 v166, v0
	v_and_b32_e32 v0, 0xffff0000, v205
	v_mul_f32_e32 v0, 0xbfb8aa3b, v0
	v_exp_f32_e32 v0, v0
	s_nop 0
	v_min_f32_e32 v147, 0x7149f2ca, v0
	v_and_b32_e32 v0, 0xffff0000, v201
	v_mul_f32_e32 v0, 0xbfb8aa3b, v0
	v_exp_f32_e32 v0, v0
	v_add_f32_e32 v146, 1.0, v146
	v_add_f32_e32 v147, 1.0, v147
	v_min_f32_e32 v0, 0x7149f2ca, v0
	v_add_f32_e32 v0, 1.0, v0
	v_rcp_f32_e32 v167, v0
	s_nop 0
	v_mul_f32_e32 v146, v146, v166
	v_mul_f32_e32 v147, v147, v167
	s_nop 0
	v_mul_f32_e32 v114, v114, v146
	v_mul_f32_e32 v115, v115, v147
	s_nop 0
	s_nop 0
	s_nop 0
	s_waitcnt vmcnt(4)
	v_lshlrev_b32_e32 v0, 16, v212
	v_mul_f32_e32 v0, 0xbfb8aa3b, v0
	v_exp_f32_e32 v0, v0
	s_nop 0
	v_min_f32_e32 v168, 0x7149f2ca, v0
	v_lshlrev_b32_e32 v0, 16, v208
	v_mul_f32_e32 v0, 0xbfb8aa3b, v0
	v_exp_f32_e32 v0, v0
	s_nop 0
	v_min_f32_e32 v0, 0x7149f2ca, v0
	v_add_f32_e32 v0, 1.0, v0
	v_rcp_f32_e32 v170, v0
	v_and_b32_e32 v0, 0xffff0000, v212
	v_mul_f32_e32 v0, 0xbfb8aa3b, v0
	v_exp_f32_e32 v0, v0
	s_nop 0
	v_min_f32_e32 v169, 0x7149f2ca, v0
	v_and_b32_e32 v0, 0xffff0000, v208
	v_mul_f32_e32 v0, 0xbfb8aa3b, v0
	v_exp_f32_e32 v0, v0
	v_add_f32_e32 v168, 1.0, v168
	v_add_f32_e32 v169, 1.0, v169
	v_min_f32_e32 v0, 0x7149f2ca, v0
	v_add_f32_e32 v0, 1.0, v0
	v_rcp_f32_e32 v171, v0
	v_lshlrev_b32_e32 v0, 16, v213
	v_mul_f32_e32 v0, 0xbfb8aa3b, v0
	v_exp_f32_e32 v0, v0
	v_mul_f32_e32 v168, v168, v170
	v_mul_f32_e32 v169, v169, v171
	v_min_f32_e32 v146, 0x7149f2ca, v0
	v_lshlrev_b32_e32 v0, 16, v209
	v_mul_f32_e32 v0, 0xbfb8aa3b, v0
	v_exp_f32_e32 v0, v0
	v_mul_f32_e32 v108, v108, v168
	v_mul_f32_e32 v109, v109, v169
	v_min_f32_e32 v0, 0x7149f2ca, v0
	v_add_f32_e32 v0, 1.0, v0
	v_rcp_f32_e32 v166, v0
	v_and_b32_e32 v0, 0xffff0000, v213
	v_mul_f32_e32 v0, 0xbfb8aa3b, v0
	v_exp_f32_e32 v0, v0
	s_nop 0
	v_min_f32_e32 v147, 0x7149f2ca, v0
	v_and_b32_e32 v0, 0xffff0000, v209
	v_mul_f32_e32 v0, 0xbfb8aa3b, v0
	v_exp_f32_e32 v0, v0
	v_add_f32_e32 v146, 1.0, v146
	v_add_f32_e32 v147, 1.0, v147
	v_min_f32_e32 v0, 0x7149f2ca, v0
	v_add_f32_e32 v0, 1.0, v0
	v_rcp_f32_e32 v167, v0
	s_nop 0
	v_mul_f32_e32 v146, v146, v166
	v_mul_f32_e32 v147, v147, v167
	s_nop 0
	v_mul_f32_e32 v110, v110, v146
	v_mul_f32_e32 v111, v111, v147
	s_nop 0
	s_nop 0
	s_nop 0
	s_waitcnt vmcnt(2)
	v_lshlrev_b32_e32 v0, 16, v220
	v_mul_f32_e32 v0, 0xbfb8aa3b, v0
	v_exp_f32_e32 v0, v0
	s_nop 0
	v_min_f32_e32 v168, 0x7149f2ca, v0
	v_lshlrev_b32_e32 v0, 16, v216
	v_mul_f32_e32 v0, 0xbfb8aa3b, v0
	v_exp_f32_e32 v0, v0
	s_nop 0
	v_min_f32_e32 v0, 0x7149f2ca, v0
	v_add_f32_e32 v0, 1.0, v0
	v_rcp_f32_e32 v170, v0
	v_and_b32_e32 v0, 0xffff0000, v220
	v_mul_f32_e32 v0, 0xbfb8aa3b, v0
	v_exp_f32_e32 v0, v0
	s_nop 0
	v_min_f32_e32 v169, 0x7149f2ca, v0
	v_and_b32_e32 v0, 0xffff0000, v216
	v_mul_f32_e32 v0, 0xbfb8aa3b, v0
	v_exp_f32_e32 v0, v0
	v_add_f32_e32 v168, 1.0, v168
	v_add_f32_e32 v169, 1.0, v169
	v_min_f32_e32 v0, 0x7149f2ca, v0
	v_add_f32_e32 v0, 1.0, v0
	v_rcp_f32_e32 v171, v0
	v_lshlrev_b32_e32 v0, 16, v221
	v_mul_f32_e32 v0, 0xbfb8aa3b, v0
	v_exp_f32_e32 v0, v0
	v_mul_f32_e32 v168, v168, v170
	v_mul_f32_e32 v169, v169, v171
	v_min_f32_e32 v146, 0x7149f2ca, v0
	v_lshlrev_b32_e32 v0, 16, v217
	v_mul_f32_e32 v0, 0xbfb8aa3b, v0
	v_exp_f32_e32 v0, v0
	v_mul_f32_e32 v104, v104, v168
	v_mul_f32_e32 v105, v105, v169
	v_min_f32_e32 v0, 0x7149f2ca, v0
	v_add_f32_e32 v0, 1.0, v0
	v_rcp_f32_e32 v166, v0
	v_and_b32_e32 v0, 0xffff0000, v221
	v_mul_f32_e32 v0, 0xbfb8aa3b, v0
	v_exp_f32_e32 v0, v0
	s_nop 0
	v_min_f32_e32 v147, 0x7149f2ca, v0
	v_and_b32_e32 v0, 0xffff0000, v217
	v_mul_f32_e32 v0, 0xbfb8aa3b, v0
	v_exp_f32_e32 v0, v0
	v_add_f32_e32 v146, 1.0, v146
	v_add_f32_e32 v147, 1.0, v147
	v_min_f32_e32 v0, 0x7149f2ca, v0
	v_add_f32_e32 v0, 1.0, v0
	v_rcp_f32_e32 v167, v0
	s_nop 0
	s_nop 0
	v_mul_f32_e32 v146, v146, v166
	v_mul_f32_e32 v147, v147, v167
	s_nop 0
	v_mul_f32_e32 v106, v106, v146
	v_mul_f32_e32 v107, v107, v147
	s_nop 0
	s_nop 0
	s_waitcnt vmcnt(0)
	v_lshlrev_b32_e32 v0, 16, v228
	v_mul_f32_e32 v0, 0xbfb8aa3b, v0
	v_exp_f32_e32 v0, v0
	s_nop 0
	v_min_f32_e32 v166, 0x7149f2ca, v0
	v_lshlrev_b32_e32 v0, 16, v224
	v_mul_f32_e32 v0, 0xbfb8aa3b, v0
	v_exp_f32_e32 v0, v0
	s_nop 0
	v_min_f32_e32 v0, 0x7149f2ca, v0
	v_add_f32_e32 v0, 1.0, v0
	v_rcp_f32_e32 v168, v0
	v_and_b32_e32 v0, 0xffff0000, v228
	v_mul_f32_e32 v0, 0xbfb8aa3b, v0
	v_exp_f32_e32 v0, v0
	s_nop 0
	v_min_f32_e32 v167, 0x7149f2ca, v0
	v_and_b32_e32 v0, 0xffff0000, v224
	v_mul_f32_e32 v0, 0xbfb8aa3b, v0
	v_exp_f32_e32 v0, v0
	v_add_f32_e32 v166, 1.0, v166
	v_add_f32_e32 v167, 1.0, v167
	v_min_f32_e32 v0, 0x7149f2ca, v0
	v_add_f32_e32 v0, 1.0, v0
	v_rcp_f32_e32 v169, v0
	v_lshlrev_b32_e32 v0, 16, v229
	v_mul_f32_e32 v0, 0xbfb8aa3b, v0
	v_exp_f32_e32 v0, v0
	v_mul_f32_e32 v166, v166, v168
	v_mul_f32_e32 v167, v167, v169
	v_min_f32_e32 v2, 0x7149f2ca, v0
	v_lshlrev_b32_e32 v0, 16, v225
	v_mul_f32_e32 v0, 0xbfb8aa3b, v0
	v_exp_f32_e32 v0, v0
	v_mul_f32_e32 v100, v100, v166
	v_mul_f32_e32 v101, v101, v167
	v_min_f32_e32 v0, 0x7149f2ca, v0
	v_add_f32_e32 v0, 1.0, v0
	v_rcp_f32_e32 v146, v0
	v_and_b32_e32 v0, 0xffff0000, v229
	v_mul_f32_e32 v0, 0xbfb8aa3b, v0
	v_exp_f32_e32 v0, v0
	s_nop 0
	v_min_f32_e32 v3, 0x7149f2ca, v0
	v_and_b32_e32 v0, 0xffff0000, v225
	v_mul_f32_e32 v0, 0xbfb8aa3b, v0
	v_exp_f32_e32 v0, v0
	v_add_f32_e32 v2, 1.0, v2
	v_add_f32_e32 v3, 1.0, v3
	v_min_f32_e32 v0, 0x7149f2ca, v0
	v_add_f32_e32 v0, 1.0, v0
	v_rcp_f32_e32 v147, v0
	v_mov_b32_e32 v0, v153
	v_mul_f32_e32 v2, v2, v146
	v_mul_f32_e32 v3, v3, v147
	s_nop 0
	v_mul_f32_e32 v102, v102, v2
	v_mul_f32_e32 v103, v103, v3
	s_nop 0
	s_nop 0
	v_mad_u64_u32 v[2:3], s[28:29], v0, s30, v[136:137]
	v_mov_b32_e32 v231, 0
	v_bfe_u32 v232, v186, 4, 1
	v_mul_u32_u24_e32 v232, 0x131fc, v232
	v_add_u32_e32 v2, v2, v232
	v_add_u32_e32 v230, s13, v2
	v_lshlrev_b64 v[232:233], 1, v[230:231]
	v_lshl_add_u64 v[198:199], s[4:5], 0, v[232:233]
	v_lshl_add_u64 v[202:203], s[8:9], 0, v[232:233]
	global_load_dwordx4 v[198:201], v[198:199], off
	global_load_dwordx4 v[202:205], v[202:203], off
	v_add_u32_e32 v230, s56, v2
	v_lshlrev_b64 v[232:233], 1, v[230:231]
	v_lshl_add_u64 v[206:207], s[4:5], 0, v[232:233]
	v_lshl_add_u64 v[210:211], s[8:9], 0, v[232:233]
	global_load_dwordx4 v[206:209], v[206:207], off
	global_load_dwordx4 v[210:213], v[210:211], off
	v_add_u32_e32 v230, s57, v2
	v_lshlrev_b64 v[232:233], 1, v[230:231]
	v_lshl_add_u64 v[214:215], s[4:5], 0, v[232:233]
	v_lshl_add_u64 v[218:219], s[8:9], 0, v[232:233]
	global_load_dwordx4 v[214:217], v[214:215], off
	global_load_dwordx4 v[218:221], v[218:219], off
	v_add_u32_e32 v230, s58, v2
	v_lshlrev_b64 v[232:233], 1, v[230:231]
	v_lshl_add_u64 v[222:223], s[4:5], 0, v[232:233]
	v_lshl_add_u64 v[226:227], s[8:9], 0, v[232:233]
	global_load_dwordx4 v[222:225], v[222:223], off
	global_load_dwordx4 v[226:229], v[226:227], off
	s_waitcnt vmcnt(6)
	v_permlane16_swap_b32_e32 v198, v200
	v_permlane16_swap_b32_e32 v199, v201
	v_permlane16_swap_b32_e32 v202, v204
	v_permlane16_swap_b32_e32 v203, v205
	v_lshlrev_b32_e32 v0, 16, v202
	v_mul_f32_e32 v0, 0xbfb8aa3b, v0
	v_exp_f32_e32 v0, v0
	s_nop 0
	v_min_f32_e32 v168, 0x7149f2ca, v0
	v_lshlrev_b32_e32 v0, 16, v198
	v_mul_f32_e32 v0, 0xbfb8aa3b, v0
	v_exp_f32_e32 v0, v0
	s_nop 0
	v_min_f32_e32 v0, 0x7149f2ca, v0
	v_add_f32_e32 v0, 1.0, v0
	v_rcp_f32_e32 v170, v0
	v_and_b32_e32 v0, 0xffff0000, v202
	v_mul_f32_e32 v0, 0xbfb8aa3b, v0
	v_exp_f32_e32 v0, v0
	s_nop 0
	v_min_f32_e32 v169, 0x7149f2ca, v0
	v_and_b32_e32 v0, 0xffff0000, v198
	v_mul_f32_e32 v0, 0xbfb8aa3b, v0
	v_exp_f32_e32 v0, v0
	v_add_f32_e32 v168, 1.0, v168
	v_add_f32_e32 v169, 1.0, v169
	v_min_f32_e32 v0, 0x7149f2ca, v0
	v_add_f32_e32 v0, 1.0, v0
	v_rcp_f32_e32 v171, v0
	v_lshlrev_b32_e32 v0, 16, v203
	v_mul_f32_e32 v0, 0xbfb8aa3b, v0
	v_exp_f32_e32 v0, v0
	v_mul_f32_e32 v168, v168, v170
	v_mul_f32_e32 v169, v169, v171
	v_min_f32_e32 v146, 0x7149f2ca, v0
	v_lshlrev_b32_e32 v0, 16, v199
	v_mul_f32_e32 v0, 0xbfb8aa3b, v0
	v_exp_f32_e32 v0, v0
	v_mul_f32_e32 v96, v96, v168
	v_mul_f32_e32 v97, v97, v169
	v_min_f32_e32 v0, 0x7149f2ca, v0
	v_add_f32_e32 v0, 1.0, v0
	v_rcp_f32_e32 v166, v0
	v_and_b32_e32 v0, 0xffff0000, v203
	v_mul_f32_e32 v0, 0xbfb8aa3b, v0
	v_exp_f32_e32 v0, v0
	s_nop 0
	v_min_f32_e32 v147, 0x7149f2ca, v0
	v_and_b32_e32 v0, 0xffff0000, v199
	v_mul_f32_e32 v0, 0xbfb8aa3b, v0
	v_exp_f32_e32 v0, v0
	v_add_f32_e32 v146, 1.0, v146
	v_add_f32_e32 v147, 1.0, v147
	v_min_f32_e32 v0, 0x7149f2ca, v0
	v_add_f32_e32 v0, 1.0, v0
	v_rcp_f32_e32 v167, v0
	s_nop 0
	v_mul_f32_e32 v146, v146, v166
	v_mul_f32_e32 v147, v147, v167
	s_nop 0
	v_mul_f32_e32 v98, v98, v146
	v_mul_f32_e32 v99, v99, v147
	s_nop 0
	s_nop 0
	s_nop 0
	s_waitcnt vmcnt(4)
	v_permlane16_swap_b32_e32 v206, v208
	v_permlane16_swap_b32_e32 v207, v209
	v_permlane16_swap_b32_e32 v210, v212
	v_permlane16_swap_b32_e32 v211, v213
	v_lshlrev_b32_e32 v0, 16, v210
	v_mul_f32_e32 v0, 0xbfb8aa3b, v0
	v_exp_f32_e32 v0, v0
	s_nop 0
	v_min_f32_e32 v168, 0x7149f2ca, v0
	v_lshlrev_b32_e32 v0, 16, v206
	v_mul_f32_e32 v0, 0xbfb8aa3b, v0
	v_exp_f32_e32 v0, v0
	s_nop 0
	v_min_f32_e32 v0, 0x7149f2ca, v0
	v_add_f32_e32 v0, 1.0, v0
	v_rcp_f32_e32 v170, v0
	v_and_b32_e32 v0, 0xffff0000, v210
	v_mul_f32_e32 v0, 0xbfb8aa3b, v0
	v_exp_f32_e32 v0, v0
	s_nop 0
	v_min_f32_e32 v169, 0x7149f2ca, v0
	v_and_b32_e32 v0, 0xffff0000, v206
	v_mul_f32_e32 v0, 0xbfb8aa3b, v0
	v_exp_f32_e32 v0, v0
	v_add_f32_e32 v168, 1.0, v168
	v_add_f32_e32 v169, 1.0, v169
	v_min_f32_e32 v0, 0x7149f2ca, v0
	v_add_f32_e32 v0, 1.0, v0
	v_rcp_f32_e32 v171, v0
	v_lshlrev_b32_e32 v0, 16, v211
	v_mul_f32_e32 v0, 0xbfb8aa3b, v0
	v_exp_f32_e32 v0, v0
	v_mul_f32_e32 v168, v168, v170
	v_mul_f32_e32 v169, v169, v171
	v_min_f32_e32 v146, 0x7149f2ca, v0
	v_lshlrev_b32_e32 v0, 16, v207
	v_mul_f32_e32 v0, 0xbfb8aa3b, v0
	v_exp_f32_e32 v0, v0
	v_mul_f32_e32 v92, v92, v168
	v_mul_f32_e32 v93, v93, v169
	v_min_f32_e32 v0, 0x7149f2ca, v0
	v_add_f32_e32 v0, 1.0, v0
	v_rcp_f32_e32 v166, v0
	v_and_b32_e32 v0, 0xffff0000, v211
	v_mul_f32_e32 v0, 0xbfb8aa3b, v0
	v_exp_f32_e32 v0, v0
	s_nop 0
	v_min_f32_e32 v147, 0x7149f2ca, v0
	v_and_b32_e32 v0, 0xffff0000, v207
	v_mul_f32_e32 v0, 0xbfb8aa3b, v0
	v_exp_f32_e32 v0, v0
	v_add_f32_e32 v146, 1.0, v146
	v_add_f32_e32 v147, 1.0, v147
	v_min_f32_e32 v0, 0x7149f2ca, v0
	v_add_f32_e32 v0, 1.0, v0
	v_rcp_f32_e32 v167, v0
	s_nop 0
	v_mul_f32_e32 v146, v146, v166
	v_mul_f32_e32 v147, v147, v167
	s_nop 0
	v_mul_f32_e32 v94, v94, v146
	v_mul_f32_e32 v95, v95, v147
	s_nop 0
	s_nop 0
	s_nop 0
	s_waitcnt vmcnt(2)
	v_permlane16_swap_b32_e32 v214, v216
	v_permlane16_swap_b32_e32 v215, v217
	v_permlane16_swap_b32_e32 v218, v220
	v_permlane16_swap_b32_e32 v219, v221
	v_lshlrev_b32_e32 v0, 16, v218
	v_mul_f32_e32 v0, 0xbfb8aa3b, v0
	v_exp_f32_e32 v0, v0
	s_nop 0
	v_min_f32_e32 v168, 0x7149f2ca, v0
	v_lshlrev_b32_e32 v0, 16, v214
	v_mul_f32_e32 v0, 0xbfb8aa3b, v0
	v_exp_f32_e32 v0, v0
	s_nop 0
	v_min_f32_e32 v0, 0x7149f2ca, v0
	v_add_f32_e32 v0, 1.0, v0
	v_rcp_f32_e32 v170, v0
	v_and_b32_e32 v0, 0xffff0000, v218
	v_mul_f32_e32 v0, 0xbfb8aa3b, v0
	v_exp_f32_e32 v0, v0
	s_nop 0
	v_min_f32_e32 v169, 0x7149f2ca, v0
	v_and_b32_e32 v0, 0xffff0000, v214
	v_mul_f32_e32 v0, 0xbfb8aa3b, v0
	v_exp_f32_e32 v0, v0
	v_add_f32_e32 v168, 1.0, v168
	v_add_f32_e32 v169, 1.0, v169
	v_min_f32_e32 v0, 0x7149f2ca, v0
	v_add_f32_e32 v0, 1.0, v0
	v_rcp_f32_e32 v171, v0
	v_lshlrev_b32_e32 v0, 16, v219
	v_mul_f32_e32 v0, 0xbfb8aa3b, v0
	v_exp_f32_e32 v0, v0
	v_mul_f32_e32 v168, v168, v170
	v_mul_f32_e32 v169, v169, v171
	v_min_f32_e32 v146, 0x7149f2ca, v0
	v_lshlrev_b32_e32 v0, 16, v215
	v_mul_f32_e32 v0, 0xbfb8aa3b, v0
	v_exp_f32_e32 v0, v0
	v_mul_f32_e32 v88, v88, v168
	v_mul_f32_e32 v89, v89, v169
	v_min_f32_e32 v0, 0x7149f2ca, v0
	v_add_f32_e32 v0, 1.0, v0
	v_rcp_f32_e32 v166, v0
	v_and_b32_e32 v0, 0xffff0000, v219
	v_mul_f32_e32 v0, 0xbfb8aa3b, v0
	v_exp_f32_e32 v0, v0
	s_nop 0
	v_min_f32_e32 v147, 0x7149f2ca, v0
	v_and_b32_e32 v0, 0xffff0000, v215
	v_mul_f32_e32 v0, 0xbfb8aa3b, v0
	v_exp_f32_e32 v0, v0
	v_add_f32_e32 v146, 1.0, v146
	v_add_f32_e32 v147, 1.0, v147
	v_min_f32_e32 v0, 0x7149f2ca, v0
	v_add_f32_e32 v0, 1.0, v0
	v_rcp_f32_e32 v167, v0
	s_nop 0
	s_nop 0
	v_mul_f32_e32 v146, v146, v166
	v_mul_f32_e32 v147, v147, v167
	s_nop 0
	v_mul_f32_e32 v90, v90, v146
	v_mul_f32_e32 v91, v91, v147
	s_nop 0
	s_nop 0
	s_waitcnt vmcnt(0)
	v_permlane16_swap_b32_e32 v222, v224
	v_permlane16_swap_b32_e32 v223, v225
	v_permlane16_swap_b32_e32 v226, v228
	v_permlane16_swap_b32_e32 v227, v229
	v_lshlrev_b32_e32 v0, 16, v226
	v_mul_f32_e32 v0, 0xbfb8aa3b, v0
	v_exp_f32_e32 v0, v0
	s_nop 0
	v_min_f32_e32 v166, 0x7149f2ca, v0
	v_lshlrev_b32_e32 v0, 16, v222
	v_mul_f32_e32 v0, 0xbfb8aa3b, v0
	v_exp_f32_e32 v0, v0
	s_nop 0
	v_min_f32_e32 v0, 0x7149f2ca, v0
	v_add_f32_e32 v0, 1.0, v0
	v_rcp_f32_e32 v168, v0
	v_and_b32_e32 v0, 0xffff0000, v226
	v_mul_f32_e32 v0, 0xbfb8aa3b, v0
	v_exp_f32_e32 v0, v0
	s_nop 0
	v_min_f32_e32 v167, 0x7149f2ca, v0
	v_and_b32_e32 v0, 0xffff0000, v222
	v_mul_f32_e32 v0, 0xbfb8aa3b, v0
	v_exp_f32_e32 v0, v0
	v_add_f32_e32 v166, 1.0, v166
	v_add_f32_e32 v167, 1.0, v167
	v_min_f32_e32 v0, 0x7149f2ca, v0
	v_add_f32_e32 v0, 1.0, v0
	v_rcp_f32_e32 v169, v0
	v_lshlrev_b32_e32 v0, 16, v227
	v_mul_f32_e32 v0, 0xbfb8aa3b, v0
	v_exp_f32_e32 v0, v0
	v_mul_f32_e32 v166, v166, v168
	v_mul_f32_e32 v167, v167, v169
	v_min_f32_e32 v2, 0x7149f2ca, v0
	v_lshlrev_b32_e32 v0, 16, v223
	v_mul_f32_e32 v0, 0xbfb8aa3b, v0
	v_exp_f32_e32 v0, v0
	v_mul_f32_e32 v84, v84, v166
	v_mul_f32_e32 v85, v85, v167
	v_min_f32_e32 v0, 0x7149f2ca, v0
	v_add_f32_e32 v0, 1.0, v0
	v_rcp_f32_e32 v146, v0
	v_and_b32_e32 v0, 0xffff0000, v227
	v_mul_f32_e32 v0, 0xbfb8aa3b, v0
	v_exp_f32_e32 v0, v0
	s_nop 0
	v_min_f32_e32 v3, 0x7149f2ca, v0
	v_and_b32_e32 v0, 0xffff0000, v223
	v_mul_f32_e32 v0, 0xbfb8aa3b, v0
	v_exp_f32_e32 v0, v0
	v_add_f32_e32 v2, 1.0, v2
	v_add_f32_e32 v3, 1.0, v3
	v_min_f32_e32 v0, 0x7149f2ca, v0
	v_add_f32_e32 v0, 1.0, v0
	v_rcp_f32_e32 v147, v0
	v_mov_b32_e32 v0, v154
	v_mul_f32_e32 v2, v2, v146
	v_mul_f32_e32 v3, v3, v147
	s_nop 0
	v_mul_f32_e32 v86, v86, v2
	v_mul_f32_e32 v87, v87, v3
	s_nop 0
	s_nop 0
	v_mad_u64_u32 v[2:3], s[28:29], v0, s30, v[136:137]
	v_lshlrev_b32_e32 v0, 16, v204
	v_mul_f32_e32 v0, 0xbfb8aa3b, v0
	v_exp_f32_e32 v0, v0
	s_nop 0
	v_min_f32_e32 v168, 0x7149f2ca, v0
	v_lshlrev_b32_e32 v0, 16, v200
	v_mul_f32_e32 v0, 0xbfb8aa3b, v0
	v_exp_f32_e32 v0, v0
	s_nop 0
	v_min_f32_e32 v0, 0x7149f2ca, v0
	v_add_f32_e32 v0, 1.0, v0
	v_rcp_f32_e32 v170, v0
	v_and_b32_e32 v0, 0xffff0000, v204
	v_mul_f32_e32 v0, 0xbfb8aa3b, v0
	v_exp_f32_e32 v0, v0
	s_nop 0
	v_min_f32_e32 v169, 0x7149f2ca, v0
	v_and_b32_e32 v0, 0xffff0000, v200
	v_mul_f32_e32 v0, 0xbfb8aa3b, v0
	v_exp_f32_e32 v0, v0
	v_add_f32_e32 v168, 1.0, v168
	v_add_f32_e32 v169, 1.0, v169
	v_min_f32_e32 v0, 0x7149f2ca, v0
	v_add_f32_e32 v0, 1.0, v0
	v_rcp_f32_e32 v171, v0
	v_lshlrev_b32_e32 v0, 16, v205
	v_mul_f32_e32 v0, 0xbfb8aa3b, v0
	v_exp_f32_e32 v0, v0
	v_mul_f32_e32 v168, v168, v170
	v_mul_f32_e32 v169, v169, v171
	v_min_f32_e32 v146, 0x7149f2ca, v0
	v_lshlrev_b32_e32 v0, 16, v201
	v_mul_f32_e32 v0, 0xbfb8aa3b, v0
	v_exp_f32_e32 v0, v0
	v_mul_f32_e32 v80, v80, v168
	v_mul_f32_e32 v81, v81, v169
	v_min_f32_e32 v0, 0x7149f2ca, v0
	v_add_f32_e32 v0, 1.0, v0
	v_rcp_f32_e32 v166, v0
	v_and_b32_e32 v0, 0xffff0000, v205
	v_mul_f32_e32 v0, 0xbfb8aa3b, v0
	v_exp_f32_e32 v0, v0
	s_nop 0
	v_min_f32_e32 v147, 0x7149f2ca, v0
	v_and_b32_e32 v0, 0xffff0000, v201
	v_mul_f32_e32 v0, 0xbfb8aa3b, v0
	v_exp_f32_e32 v0, v0
	v_add_f32_e32 v146, 1.0, v146
	v_add_f32_e32 v147, 1.0, v147
	v_min_f32_e32 v0, 0x7149f2ca, v0
	v_add_f32_e32 v0, 1.0, v0
	v_rcp_f32_e32 v167, v0
	s_nop 0
	v_mul_f32_e32 v146, v146, v166
	v_mul_f32_e32 v147, v147, v167
	s_nop 0
	v_mul_f32_e32 v82, v82, v146
	v_mul_f32_e32 v83, v83, v147
	s_nop 0
	s_nop 0
	s_nop 0
	s_waitcnt vmcnt(4)
	v_lshlrev_b32_e32 v0, 16, v212
	v_mul_f32_e32 v0, 0xbfb8aa3b, v0
	v_exp_f32_e32 v0, v0
	s_nop 0
	v_min_f32_e32 v168, 0x7149f2ca, v0
	v_lshlrev_b32_e32 v0, 16, v208
	v_mul_f32_e32 v0, 0xbfb8aa3b, v0
	v_exp_f32_e32 v0, v0
	s_nop 0
	v_min_f32_e32 v0, 0x7149f2ca, v0
	v_add_f32_e32 v0, 1.0, v0
	v_rcp_f32_e32 v170, v0
	v_and_b32_e32 v0, 0xffff0000, v212
	v_mul_f32_e32 v0, 0xbfb8aa3b, v0
	v_exp_f32_e32 v0, v0
	s_nop 0
	v_min_f32_e32 v169, 0x7149f2ca, v0
	v_and_b32_e32 v0, 0xffff0000, v208
	v_mul_f32_e32 v0, 0xbfb8aa3b, v0
	v_exp_f32_e32 v0, v0
	v_add_f32_e32 v168, 1.0, v168
	v_add_f32_e32 v169, 1.0, v169
	v_min_f32_e32 v0, 0x7149f2ca, v0
	v_add_f32_e32 v0, 1.0, v0
	v_rcp_f32_e32 v171, v0
	v_lshlrev_b32_e32 v0, 16, v213
	v_mul_f32_e32 v0, 0xbfb8aa3b, v0
	v_exp_f32_e32 v0, v0
	v_mul_f32_e32 v168, v168, v170
	v_mul_f32_e32 v169, v169, v171
	v_min_f32_e32 v146, 0x7149f2ca, v0
	v_lshlrev_b32_e32 v0, 16, v209
	v_mul_f32_e32 v0, 0xbfb8aa3b, v0
	v_exp_f32_e32 v0, v0
	v_mul_f32_e32 v76, v76, v168
	v_mul_f32_e32 v77, v77, v169
	v_min_f32_e32 v0, 0x7149f2ca, v0
	v_add_f32_e32 v0, 1.0, v0
	v_rcp_f32_e32 v166, v0
	v_and_b32_e32 v0, 0xffff0000, v213
	v_mul_f32_e32 v0, 0xbfb8aa3b, v0
	v_exp_f32_e32 v0, v0
	s_nop 0
	v_min_f32_e32 v147, 0x7149f2ca, v0
	v_and_b32_e32 v0, 0xffff0000, v209
	v_mul_f32_e32 v0, 0xbfb8aa3b, v0
	v_exp_f32_e32 v0, v0
	v_add_f32_e32 v146, 1.0, v146
	v_add_f32_e32 v147, 1.0, v147
	v_min_f32_e32 v0, 0x7149f2ca, v0
	v_add_f32_e32 v0, 1.0, v0
	v_rcp_f32_e32 v167, v0
	s_nop 0
	v_mul_f32_e32 v146, v146, v166
	v_mul_f32_e32 v147, v147, v167
	s_nop 0
	v_mul_f32_e32 v78, v78, v146
	v_mul_f32_e32 v79, v79, v147
	s_nop 0
	s_nop 0
	s_nop 0
	s_waitcnt vmcnt(2)
	v_lshlrev_b32_e32 v0, 16, v220
	v_mul_f32_e32 v0, 0xbfb8aa3b, v0
	v_exp_f32_e32 v0, v0
	s_nop 0
	v_min_f32_e32 v168, 0x7149f2ca, v0
	v_lshlrev_b32_e32 v0, 16, v216
	v_mul_f32_e32 v0, 0xbfb8aa3b, v0
	v_exp_f32_e32 v0, v0
	s_nop 0
	v_min_f32_e32 v0, 0x7149f2ca, v0
	v_add_f32_e32 v0, 1.0, v0
	v_rcp_f32_e32 v170, v0
	v_and_b32_e32 v0, 0xffff0000, v220
	v_mul_f32_e32 v0, 0xbfb8aa3b, v0
	v_exp_f32_e32 v0, v0
	s_nop 0
	v_min_f32_e32 v169, 0x7149f2ca, v0
	v_and_b32_e32 v0, 0xffff0000, v216
	v_mul_f32_e32 v0, 0xbfb8aa3b, v0
	v_exp_f32_e32 v0, v0
	v_add_f32_e32 v168, 1.0, v168
	v_add_f32_e32 v169, 1.0, v169
	v_min_f32_e32 v0, 0x7149f2ca, v0
	v_add_f32_e32 v0, 1.0, v0
	v_rcp_f32_e32 v171, v0
	v_lshlrev_b32_e32 v0, 16, v221
	v_mul_f32_e32 v0, 0xbfb8aa3b, v0
	v_exp_f32_e32 v0, v0
	v_mul_f32_e32 v168, v168, v170
	v_mul_f32_e32 v169, v169, v171
	v_min_f32_e32 v146, 0x7149f2ca, v0
	v_lshlrev_b32_e32 v0, 16, v217
	v_mul_f32_e32 v0, 0xbfb8aa3b, v0
	v_exp_f32_e32 v0, v0
	v_mul_f32_e32 v72, v72, v168
	v_mul_f32_e32 v73, v73, v169
	v_min_f32_e32 v0, 0x7149f2ca, v0
	v_add_f32_e32 v0, 1.0, v0
	v_rcp_f32_e32 v166, v0
	v_and_b32_e32 v0, 0xffff0000, v221
	v_mul_f32_e32 v0, 0xbfb8aa3b, v0
	v_exp_f32_e32 v0, v0
	s_nop 0
	v_min_f32_e32 v147, 0x7149f2ca, v0
	v_and_b32_e32 v0, 0xffff0000, v217
	v_mul_f32_e32 v0, 0xbfb8aa3b, v0
	v_exp_f32_e32 v0, v0
	v_add_f32_e32 v146, 1.0, v146
	v_add_f32_e32 v147, 1.0, v147
	v_min_f32_e32 v0, 0x7149f2ca, v0
	v_add_f32_e32 v0, 1.0, v0
	v_rcp_f32_e32 v167, v0
	s_nop 0
	s_nop 0
	v_mul_f32_e32 v146, v146, v166
	v_mul_f32_e32 v147, v147, v167
	s_nop 0
	v_mul_f32_e32 v74, v74, v146
	v_mul_f32_e32 v75, v75, v147
	s_nop 0
	s_nop 0
	s_waitcnt vmcnt(0)
	v_lshlrev_b32_e32 v0, 16, v228
	v_mul_f32_e32 v0, 0xbfb8aa3b, v0
	v_exp_f32_e32 v0, v0
	s_nop 0
	v_min_f32_e32 v166, 0x7149f2ca, v0
	v_lshlrev_b32_e32 v0, 16, v224
	v_mul_f32_e32 v0, 0xbfb8aa3b, v0
	v_exp_f32_e32 v0, v0
	s_nop 0
	v_min_f32_e32 v0, 0x7149f2ca, v0
	v_add_f32_e32 v0, 1.0, v0
	v_rcp_f32_e32 v168, v0
	v_and_b32_e32 v0, 0xffff0000, v228
	v_mul_f32_e32 v0, 0xbfb8aa3b, v0
	v_exp_f32_e32 v0, v0
	s_nop 0
	v_min_f32_e32 v167, 0x7149f2ca, v0
	v_and_b32_e32 v0, 0xffff0000, v224
	v_mul_f32_e32 v0, 0xbfb8aa3b, v0
	v_exp_f32_e32 v0, v0
	v_add_f32_e32 v166, 1.0, v166
	v_add_f32_e32 v167, 1.0, v167
	v_min_f32_e32 v0, 0x7149f2ca, v0
	v_add_f32_e32 v0, 1.0, v0
	v_rcp_f32_e32 v169, v0
	v_lshlrev_b32_e32 v0, 16, v229
	v_mul_f32_e32 v0, 0xbfb8aa3b, v0
	v_exp_f32_e32 v0, v0
	v_mul_f32_e32 v166, v166, v168
	v_mul_f32_e32 v167, v167, v169
	v_min_f32_e32 v2, 0x7149f2ca, v0
	v_lshlrev_b32_e32 v0, 16, v225
	v_mul_f32_e32 v0, 0xbfb8aa3b, v0
	v_exp_f32_e32 v0, v0
	v_mul_f32_e32 v68, v68, v166
	v_mul_f32_e32 v69, v69, v167
	v_min_f32_e32 v0, 0x7149f2ca, v0
	v_add_f32_e32 v0, 1.0, v0
	v_rcp_f32_e32 v146, v0
	v_and_b32_e32 v0, 0xffff0000, v229
	v_mul_f32_e32 v0, 0xbfb8aa3b, v0
	v_exp_f32_e32 v0, v0
	s_nop 0
	v_min_f32_e32 v3, 0x7149f2ca, v0
	v_and_b32_e32 v0, 0xffff0000, v225
	v_mul_f32_e32 v0, 0xbfb8aa3b, v0
	v_exp_f32_e32 v0, v0
	v_add_f32_e32 v2, 1.0, v2
	v_add_f32_e32 v3, 1.0, v3
	v_min_f32_e32 v0, 0x7149f2ca, v0
	v_add_f32_e32 v0, 1.0, v0
	v_rcp_f32_e32 v147, v0
	v_mov_b32_e32 v0, v155
	v_mul_f32_e32 v2, v2, v146
	v_mul_f32_e32 v3, v3, v147
	s_nop 0
	v_mul_f32_e32 v70, v70, v2
	v_mul_f32_e32 v71, v71, v3
	s_nop 0
	s_nop 0
	v_mad_u64_u32 v[2:3], s[28:29], v0, s30, v[136:137]
	v_mov_b32_e32 v231, 0
	v_bfe_u32 v232, v186, 4, 1
	v_mul_u32_u24_e32 v232, 0x131fc, v232
	v_add_u32_e32 v2, v2, v232
	v_add_u32_e32 v230, s13, v2
	v_lshlrev_b64 v[232:233], 1, v[230:231]
	v_lshl_add_u64 v[198:199], s[4:5], 0, v[232:233]
	v_lshl_add_u64 v[202:203], s[8:9], 0, v[232:233]
	global_load_dwordx4 v[198:201], v[198:199], off
	global_load_dwordx4 v[202:205], v[202:203], off
	v_add_u32_e32 v230, s56, v2
	v_lshlrev_b64 v[232:233], 1, v[230:231]
	v_lshl_add_u64 v[206:207], s[4:5], 0, v[232:233]
	v_lshl_add_u64 v[210:211], s[8:9], 0, v[232:233]
	global_load_dwordx4 v[206:209], v[206:207], off
	global_load_dwordx4 v[210:213], v[210:211], off
	v_add_u32_e32 v230, s57, v2
	v_lshlrev_b64 v[232:233], 1, v[230:231]
	v_lshl_add_u64 v[214:215], s[4:5], 0, v[232:233]
	v_lshl_add_u64 v[218:219], s[8:9], 0, v[232:233]
	global_load_dwordx4 v[214:217], v[214:215], off
	global_load_dwordx4 v[218:221], v[218:219], off
	v_add_u32_e32 v230, s58, v2
	v_lshlrev_b64 v[232:233], 1, v[230:231]
	v_lshl_add_u64 v[222:223], s[4:5], 0, v[232:233]
	v_lshl_add_u64 v[226:227], s[8:9], 0, v[232:233]
	global_load_dwordx4 v[222:225], v[222:223], off
	global_load_dwordx4 v[226:229], v[226:227], off
	s_waitcnt vmcnt(6)
	v_permlane16_swap_b32_e32 v198, v200
	v_permlane16_swap_b32_e32 v199, v201
	v_permlane16_swap_b32_e32 v202, v204
	v_permlane16_swap_b32_e32 v203, v205
	v_lshlrev_b32_e32 v0, 16, v202
	v_mul_f32_e32 v0, 0xbfb8aa3b, v0
	v_exp_f32_e32 v0, v0
	s_nop 0
	v_min_f32_e32 v168, 0x7149f2ca, v0
	v_lshlrev_b32_e32 v0, 16, v198
	v_mul_f32_e32 v0, 0xbfb8aa3b, v0
	v_exp_f32_e32 v0, v0
	s_nop 0
	v_min_f32_e32 v0, 0x7149f2ca, v0
	v_add_f32_e32 v0, 1.0, v0
	v_rcp_f32_e32 v170, v0
	v_and_b32_e32 v0, 0xffff0000, v202
	v_mul_f32_e32 v0, 0xbfb8aa3b, v0
	v_exp_f32_e32 v0, v0
	s_nop 0
	v_min_f32_e32 v169, 0x7149f2ca, v0
	v_and_b32_e32 v0, 0xffff0000, v198
	v_mul_f32_e32 v0, 0xbfb8aa3b, v0
	v_exp_f32_e32 v0, v0
	v_add_f32_e32 v168, 1.0, v168
	v_add_f32_e32 v169, 1.0, v169
	v_min_f32_e32 v0, 0x7149f2ca, v0
	v_add_f32_e32 v0, 1.0, v0
	v_rcp_f32_e32 v171, v0
	v_lshlrev_b32_e32 v0, 16, v203
	v_mul_f32_e32 v0, 0xbfb8aa3b, v0
	v_exp_f32_e32 v0, v0
	v_mul_f32_e32 v168, v168, v170
	v_mul_f32_e32 v169, v169, v171
	v_min_f32_e32 v146, 0x7149f2ca, v0
	v_lshlrev_b32_e32 v0, 16, v199
	v_mul_f32_e32 v0, 0xbfb8aa3b, v0
	v_exp_f32_e32 v0, v0
	v_mul_f32_e32 v64, v64, v168
	v_mul_f32_e32 v65, v65, v169
	v_min_f32_e32 v0, 0x7149f2ca, v0
	v_add_f32_e32 v0, 1.0, v0
	v_rcp_f32_e32 v166, v0
	v_and_b32_e32 v0, 0xffff0000, v203
	v_mul_f32_e32 v0, 0xbfb8aa3b, v0
	v_exp_f32_e32 v0, v0
	s_nop 0
	v_min_f32_e32 v147, 0x7149f2ca, v0
	v_and_b32_e32 v0, 0xffff0000, v199
	v_mul_f32_e32 v0, 0xbfb8aa3b, v0
	v_exp_f32_e32 v0, v0
	v_add_f32_e32 v146, 1.0, v146
	v_add_f32_e32 v147, 1.0, v147
	v_min_f32_e32 v0, 0x7149f2ca, v0
	v_add_f32_e32 v0, 1.0, v0
	v_rcp_f32_e32 v167, v0
	s_nop 0
	v_mul_f32_e32 v146, v146, v166
	v_mul_f32_e32 v147, v147, v167
	s_nop 0
	v_mul_f32_e32 v66, v66, v146
	v_mul_f32_e32 v67, v67, v147
	s_nop 0
	s_nop 0
	s_nop 0
	s_waitcnt vmcnt(4)
	v_permlane16_swap_b32_e32 v206, v208
	v_permlane16_swap_b32_e32 v207, v209
	v_permlane16_swap_b32_e32 v210, v212
	v_permlane16_swap_b32_e32 v211, v213
	v_lshlrev_b32_e32 v0, 16, v210
	v_mul_f32_e32 v0, 0xbfb8aa3b, v0
	v_exp_f32_e32 v0, v0
	s_nop 0
	v_min_f32_e32 v168, 0x7149f2ca, v0
	v_lshlrev_b32_e32 v0, 16, v206
	v_mul_f32_e32 v0, 0xbfb8aa3b, v0
	v_exp_f32_e32 v0, v0
	s_nop 0
	v_min_f32_e32 v0, 0x7149f2ca, v0
	v_add_f32_e32 v0, 1.0, v0
	v_rcp_f32_e32 v170, v0
	v_and_b32_e32 v0, 0xffff0000, v210
	v_mul_f32_e32 v0, 0xbfb8aa3b, v0
	v_exp_f32_e32 v0, v0
	s_nop 0
	v_min_f32_e32 v169, 0x7149f2ca, v0
	v_and_b32_e32 v0, 0xffff0000, v206
	v_mul_f32_e32 v0, 0xbfb8aa3b, v0
	v_exp_f32_e32 v0, v0
	v_add_f32_e32 v168, 1.0, v168
	v_add_f32_e32 v169, 1.0, v169
	v_min_f32_e32 v0, 0x7149f2ca, v0
	v_add_f32_e32 v0, 1.0, v0
	v_rcp_f32_e32 v171, v0
	v_lshlrev_b32_e32 v0, 16, v211
	v_mul_f32_e32 v0, 0xbfb8aa3b, v0
	v_exp_f32_e32 v0, v0
	v_mul_f32_e32 v168, v168, v170
	v_mul_f32_e32 v169, v169, v171
	v_min_f32_e32 v146, 0x7149f2ca, v0
	v_lshlrev_b32_e32 v0, 16, v207
	v_mul_f32_e32 v0, 0xbfb8aa3b, v0
	v_exp_f32_e32 v0, v0
	v_mul_f32_e32 v60, v60, v168
	v_mul_f32_e32 v61, v61, v169
	v_min_f32_e32 v0, 0x7149f2ca, v0
	v_add_f32_e32 v0, 1.0, v0
	v_rcp_f32_e32 v166, v0
	v_and_b32_e32 v0, 0xffff0000, v211
	v_mul_f32_e32 v0, 0xbfb8aa3b, v0
	v_exp_f32_e32 v0, v0
	s_nop 0
	v_min_f32_e32 v147, 0x7149f2ca, v0
	v_and_b32_e32 v0, 0xffff0000, v207
	v_mul_f32_e32 v0, 0xbfb8aa3b, v0
	v_exp_f32_e32 v0, v0
	v_add_f32_e32 v146, 1.0, v146
	v_add_f32_e32 v147, 1.0, v147
	v_min_f32_e32 v0, 0x7149f2ca, v0
	v_add_f32_e32 v0, 1.0, v0
	v_rcp_f32_e32 v167, v0
	s_nop 0
	v_mul_f32_e32 v146, v146, v166
	v_mul_f32_e32 v147, v147, v167
	s_nop 0
	v_mul_f32_e32 v62, v62, v146
	v_mul_f32_e32 v63, v63, v147
	s_nop 0
	s_nop 0
	s_nop 0
	s_waitcnt vmcnt(2)
	v_permlane16_swap_b32_e32 v214, v216
	v_permlane16_swap_b32_e32 v215, v217
	v_permlane16_swap_b32_e32 v218, v220
	v_permlane16_swap_b32_e32 v219, v221
	v_lshlrev_b32_e32 v0, 16, v218
	v_mul_f32_e32 v0, 0xbfb8aa3b, v0
	v_exp_f32_e32 v0, v0
	s_nop 0
	v_min_f32_e32 v168, 0x7149f2ca, v0
	v_lshlrev_b32_e32 v0, 16, v214
	v_mul_f32_e32 v0, 0xbfb8aa3b, v0
	v_exp_f32_e32 v0, v0
	s_nop 0
	v_min_f32_e32 v0, 0x7149f2ca, v0
	v_add_f32_e32 v0, 1.0, v0
	v_rcp_f32_e32 v170, v0
	v_and_b32_e32 v0, 0xffff0000, v218
	v_mul_f32_e32 v0, 0xbfb8aa3b, v0
	v_exp_f32_e32 v0, v0
	s_nop 0
	v_min_f32_e32 v169, 0x7149f2ca, v0
	v_and_b32_e32 v0, 0xffff0000, v214
	v_mul_f32_e32 v0, 0xbfb8aa3b, v0
	v_exp_f32_e32 v0, v0
	v_add_f32_e32 v168, 1.0, v168
	v_add_f32_e32 v169, 1.0, v169
	v_min_f32_e32 v0, 0x7149f2ca, v0
	v_add_f32_e32 v0, 1.0, v0
	v_rcp_f32_e32 v171, v0
	v_lshlrev_b32_e32 v0, 16, v219
	v_mul_f32_e32 v0, 0xbfb8aa3b, v0
	v_exp_f32_e32 v0, v0
	v_mul_f32_e32 v168, v168, v170
	v_mul_f32_e32 v169, v169, v171
	v_min_f32_e32 v146, 0x7149f2ca, v0
	v_lshlrev_b32_e32 v0, 16, v215
	v_mul_f32_e32 v0, 0xbfb8aa3b, v0
	v_exp_f32_e32 v0, v0
	v_mul_f32_e32 v56, v56, v168
	v_mul_f32_e32 v57, v57, v169
	v_min_f32_e32 v0, 0x7149f2ca, v0
	v_add_f32_e32 v0, 1.0, v0
	v_rcp_f32_e32 v166, v0
	v_and_b32_e32 v0, 0xffff0000, v219
	v_mul_f32_e32 v0, 0xbfb8aa3b, v0
	v_exp_f32_e32 v0, v0
	s_nop 0
	v_min_f32_e32 v147, 0x7149f2ca, v0
	v_and_b32_e32 v0, 0xffff0000, v215
	v_mul_f32_e32 v0, 0xbfb8aa3b, v0
	v_exp_f32_e32 v0, v0
	v_add_f32_e32 v146, 1.0, v146
	v_add_f32_e32 v147, 1.0, v147
	v_min_f32_e32 v0, 0x7149f2ca, v0
	v_add_f32_e32 v0, 1.0, v0
	v_rcp_f32_e32 v167, v0
	s_nop 0
	s_nop 0
	v_mul_f32_e32 v146, v146, v166
	v_mul_f32_e32 v147, v147, v167
	s_nop 0
	v_mul_f32_e32 v58, v58, v146
	v_mul_f32_e32 v59, v59, v147
	s_nop 0
	s_nop 0
	s_waitcnt vmcnt(0)
	v_permlane16_swap_b32_e32 v222, v224
	v_permlane16_swap_b32_e32 v223, v225
	v_permlane16_swap_b32_e32 v226, v228
	v_permlane16_swap_b32_e32 v227, v229
	v_lshlrev_b32_e32 v0, 16, v226
	v_mul_f32_e32 v0, 0xbfb8aa3b, v0
	v_exp_f32_e32 v0, v0
	s_nop 0
	v_min_f32_e32 v166, 0x7149f2ca, v0
	v_lshlrev_b32_e32 v0, 16, v222
	v_mul_f32_e32 v0, 0xbfb8aa3b, v0
	v_exp_f32_e32 v0, v0
	s_nop 0
	v_min_f32_e32 v0, 0x7149f2ca, v0
	v_add_f32_e32 v0, 1.0, v0
	v_rcp_f32_e32 v168, v0
	v_and_b32_e32 v0, 0xffff0000, v226
	v_mul_f32_e32 v0, 0xbfb8aa3b, v0
	v_exp_f32_e32 v0, v0
	s_nop 0
	v_min_f32_e32 v167, 0x7149f2ca, v0
	v_and_b32_e32 v0, 0xffff0000, v222
	v_mul_f32_e32 v0, 0xbfb8aa3b, v0
	v_exp_f32_e32 v0, v0
	v_add_f32_e32 v166, 1.0, v166
	v_add_f32_e32 v167, 1.0, v167
	v_min_f32_e32 v0, 0x7149f2ca, v0
	v_add_f32_e32 v0, 1.0, v0
	v_rcp_f32_e32 v169, v0
	v_lshlrev_b32_e32 v0, 16, v227
	v_mul_f32_e32 v0, 0xbfb8aa3b, v0
	v_exp_f32_e32 v0, v0
	v_mul_f32_e32 v166, v166, v168
	v_mul_f32_e32 v167, v167, v169
	v_min_f32_e32 v2, 0x7149f2ca, v0
	v_lshlrev_b32_e32 v0, 16, v223
	v_mul_f32_e32 v0, 0xbfb8aa3b, v0
	v_exp_f32_e32 v0, v0
	v_mul_f32_e32 v52, v52, v166
	v_mul_f32_e32 v53, v53, v167
	v_min_f32_e32 v0, 0x7149f2ca, v0
	v_add_f32_e32 v0, 1.0, v0
	v_rcp_f32_e32 v146, v0
	v_and_b32_e32 v0, 0xffff0000, v227
	v_mul_f32_e32 v0, 0xbfb8aa3b, v0
	v_exp_f32_e32 v0, v0
	s_nop 0
	v_min_f32_e32 v3, 0x7149f2ca, v0
	v_and_b32_e32 v0, 0xffff0000, v223
	v_mul_f32_e32 v0, 0xbfb8aa3b, v0
	v_exp_f32_e32 v0, v0
	v_add_f32_e32 v2, 1.0, v2
	v_add_f32_e32 v3, 1.0, v3
	v_min_f32_e32 v0, 0x7149f2ca, v0
	v_add_f32_e32 v0, 1.0, v0
	v_rcp_f32_e32 v147, v0
	v_mov_b32_e32 v0, v156
	v_mul_f32_e32 v2, v2, v146
	v_mul_f32_e32 v3, v3, v147
	s_nop 0
	v_mul_f32_e32 v54, v54, v2
	v_mul_f32_e32 v55, v55, v3
	s_nop 0
	s_nop 0
	v_mad_u64_u32 v[2:3], s[28:29], v0, s30, v[136:137]
	v_lshlrev_b32_e32 v0, 16, v204
	v_mul_f32_e32 v0, 0xbfb8aa3b, v0
	v_exp_f32_e32 v0, v0
	s_nop 0
	v_min_f32_e32 v168, 0x7149f2ca, v0
	v_lshlrev_b32_e32 v0, 16, v200
	v_mul_f32_e32 v0, 0xbfb8aa3b, v0
	v_exp_f32_e32 v0, v0
	s_nop 0
	v_min_f32_e32 v0, 0x7149f2ca, v0
	v_add_f32_e32 v0, 1.0, v0
	v_rcp_f32_e32 v170, v0
	v_and_b32_e32 v0, 0xffff0000, v204
	v_mul_f32_e32 v0, 0xbfb8aa3b, v0
	v_exp_f32_e32 v0, v0
	s_nop 0
	v_min_f32_e32 v169, 0x7149f2ca, v0
	v_and_b32_e32 v0, 0xffff0000, v200
	v_mul_f32_e32 v0, 0xbfb8aa3b, v0
	v_exp_f32_e32 v0, v0
	v_add_f32_e32 v168, 1.0, v168
	v_add_f32_e32 v169, 1.0, v169
	v_min_f32_e32 v0, 0x7149f2ca, v0
	v_add_f32_e32 v0, 1.0, v0
	v_rcp_f32_e32 v171, v0
	v_lshlrev_b32_e32 v0, 16, v205
	v_mul_f32_e32 v0, 0xbfb8aa3b, v0
	v_exp_f32_e32 v0, v0
	v_mul_f32_e32 v168, v168, v170
	v_mul_f32_e32 v169, v169, v171
	v_min_f32_e32 v146, 0x7149f2ca, v0
	v_lshlrev_b32_e32 v0, 16, v201
	v_mul_f32_e32 v0, 0xbfb8aa3b, v0
	v_exp_f32_e32 v0, v0
	v_mul_f32_e32 v48, v48, v168
	v_mul_f32_e32 v49, v49, v169
	v_min_f32_e32 v0, 0x7149f2ca, v0
	v_add_f32_e32 v0, 1.0, v0
	v_rcp_f32_e32 v166, v0
	v_and_b32_e32 v0, 0xffff0000, v205
	v_mul_f32_e32 v0, 0xbfb8aa3b, v0
	v_exp_f32_e32 v0, v0
	s_nop 0
	v_min_f32_e32 v147, 0x7149f2ca, v0
	v_and_b32_e32 v0, 0xffff0000, v201
	v_mul_f32_e32 v0, 0xbfb8aa3b, v0
	v_exp_f32_e32 v0, v0
	v_add_f32_e32 v146, 1.0, v146
	v_add_f32_e32 v147, 1.0, v147
	v_min_f32_e32 v0, 0x7149f2ca, v0
	v_add_f32_e32 v0, 1.0, v0
	v_rcp_f32_e32 v167, v0
	s_nop 0
	v_mul_f32_e32 v146, v146, v166
	v_mul_f32_e32 v147, v147, v167
	s_nop 0
	v_mul_f32_e32 v50, v50, v146
	v_mul_f32_e32 v51, v51, v147
	s_nop 0
	s_nop 0
	s_nop 0
	s_waitcnt vmcnt(4)
	v_lshlrev_b32_e32 v0, 16, v212
	v_mul_f32_e32 v0, 0xbfb8aa3b, v0
	v_exp_f32_e32 v0, v0
	s_nop 0
	v_min_f32_e32 v168, 0x7149f2ca, v0
	v_lshlrev_b32_e32 v0, 16, v208
	v_mul_f32_e32 v0, 0xbfb8aa3b, v0
	v_exp_f32_e32 v0, v0
	s_nop 0
	v_min_f32_e32 v0, 0x7149f2ca, v0
	v_add_f32_e32 v0, 1.0, v0
	v_rcp_f32_e32 v170, v0
	v_and_b32_e32 v0, 0xffff0000, v212
	v_mul_f32_e32 v0, 0xbfb8aa3b, v0
	v_exp_f32_e32 v0, v0
	s_nop 0
	v_min_f32_e32 v169, 0x7149f2ca, v0
	v_and_b32_e32 v0, 0xffff0000, v208
	v_mul_f32_e32 v0, 0xbfb8aa3b, v0
	v_exp_f32_e32 v0, v0
	v_add_f32_e32 v168, 1.0, v168
	v_add_f32_e32 v169, 1.0, v169
	v_min_f32_e32 v0, 0x7149f2ca, v0
	v_add_f32_e32 v0, 1.0, v0
	v_rcp_f32_e32 v171, v0
	v_lshlrev_b32_e32 v0, 16, v213
	v_mul_f32_e32 v0, 0xbfb8aa3b, v0
	v_exp_f32_e32 v0, v0
	v_mul_f32_e32 v168, v168, v170
	v_mul_f32_e32 v169, v169, v171
	v_min_f32_e32 v146, 0x7149f2ca, v0
	v_lshlrev_b32_e32 v0, 16, v209
	v_mul_f32_e32 v0, 0xbfb8aa3b, v0
	v_exp_f32_e32 v0, v0
	v_mul_f32_e32 v44, v44, v168
	v_mul_f32_e32 v45, v45, v169
	v_min_f32_e32 v0, 0x7149f2ca, v0
	v_add_f32_e32 v0, 1.0, v0
	v_rcp_f32_e32 v166, v0
	v_and_b32_e32 v0, 0xffff0000, v213
	v_mul_f32_e32 v0, 0xbfb8aa3b, v0
	v_exp_f32_e32 v0, v0
	s_nop 0
	v_min_f32_e32 v147, 0x7149f2ca, v0
	v_and_b32_e32 v0, 0xffff0000, v209
	v_mul_f32_e32 v0, 0xbfb8aa3b, v0
	v_exp_f32_e32 v0, v0
	v_add_f32_e32 v146, 1.0, v146
	v_add_f32_e32 v147, 1.0, v147
	v_min_f32_e32 v0, 0x7149f2ca, v0
	v_add_f32_e32 v0, 1.0, v0
	v_rcp_f32_e32 v167, v0
	s_nop 0
	v_mul_f32_e32 v146, v146, v166
	v_mul_f32_e32 v147, v147, v167
	s_nop 0
	v_mul_f32_e32 v46, v46, v146
	v_mul_f32_e32 v47, v47, v147
	s_nop 0
	s_nop 0
	s_nop 0
	s_waitcnt vmcnt(2)
	v_lshlrev_b32_e32 v0, 16, v220
	v_mul_f32_e32 v0, 0xbfb8aa3b, v0
	v_exp_f32_e32 v0, v0
	s_nop 0
	v_min_f32_e32 v168, 0x7149f2ca, v0
	v_lshlrev_b32_e32 v0, 16, v216
	v_mul_f32_e32 v0, 0xbfb8aa3b, v0
	v_exp_f32_e32 v0, v0
	s_nop 0
	v_min_f32_e32 v0, 0x7149f2ca, v0
	v_add_f32_e32 v0, 1.0, v0
	v_rcp_f32_e32 v170, v0
	v_and_b32_e32 v0, 0xffff0000, v220
	v_mul_f32_e32 v0, 0xbfb8aa3b, v0
	v_exp_f32_e32 v0, v0
	s_nop 0
	v_min_f32_e32 v169, 0x7149f2ca, v0
	v_and_b32_e32 v0, 0xffff0000, v216
	v_mul_f32_e32 v0, 0xbfb8aa3b, v0
	v_exp_f32_e32 v0, v0
	v_add_f32_e32 v168, 1.0, v168
	v_add_f32_e32 v169, 1.0, v169
	v_min_f32_e32 v0, 0x7149f2ca, v0
	v_add_f32_e32 v0, 1.0, v0
	v_rcp_f32_e32 v171, v0
	v_lshlrev_b32_e32 v0, 16, v221
	v_mul_f32_e32 v0, 0xbfb8aa3b, v0
	v_exp_f32_e32 v0, v0
	v_mul_f32_e32 v168, v168, v170
	v_mul_f32_e32 v169, v169, v171
	v_min_f32_e32 v146, 0x7149f2ca, v0
	v_lshlrev_b32_e32 v0, 16, v217
	v_mul_f32_e32 v0, 0xbfb8aa3b, v0
	v_exp_f32_e32 v0, v0
	v_mul_f32_e32 v40, v40, v168
	v_mul_f32_e32 v41, v41, v169
	v_min_f32_e32 v0, 0x7149f2ca, v0
	v_add_f32_e32 v0, 1.0, v0
	v_rcp_f32_e32 v166, v0
	v_and_b32_e32 v0, 0xffff0000, v221
	v_mul_f32_e32 v0, 0xbfb8aa3b, v0
	v_exp_f32_e32 v0, v0
	s_nop 0
	v_min_f32_e32 v147, 0x7149f2ca, v0
	v_and_b32_e32 v0, 0xffff0000, v217
	v_mul_f32_e32 v0, 0xbfb8aa3b, v0
	v_exp_f32_e32 v0, v0
	v_add_f32_e32 v146, 1.0, v146
	v_add_f32_e32 v147, 1.0, v147
	v_min_f32_e32 v0, 0x7149f2ca, v0
	v_add_f32_e32 v0, 1.0, v0
	v_rcp_f32_e32 v167, v0
	s_nop 0
	s_nop 0
	v_mul_f32_e32 v146, v146, v166
	v_mul_f32_e32 v147, v147, v167
	s_nop 0
	v_mul_f32_e32 v42, v42, v146
	v_mul_f32_e32 v43, v43, v147
	s_nop 0
	s_nop 0
	s_waitcnt vmcnt(0)
	v_lshlrev_b32_e32 v0, 16, v228
	v_mul_f32_e32 v0, 0xbfb8aa3b, v0
	v_exp_f32_e32 v0, v0
	s_nop 0
	v_min_f32_e32 v166, 0x7149f2ca, v0
	v_lshlrev_b32_e32 v0, 16, v224
	v_mul_f32_e32 v0, 0xbfb8aa3b, v0
	v_exp_f32_e32 v0, v0
	s_nop 0
	v_min_f32_e32 v0, 0x7149f2ca, v0
	v_add_f32_e32 v0, 1.0, v0
	v_rcp_f32_e32 v168, v0
	v_and_b32_e32 v0, 0xffff0000, v228
	v_mul_f32_e32 v0, 0xbfb8aa3b, v0
	v_exp_f32_e32 v0, v0
	s_nop 0
	v_min_f32_e32 v167, 0x7149f2ca, v0
	v_and_b32_e32 v0, 0xffff0000, v224
	v_mul_f32_e32 v0, 0xbfb8aa3b, v0
	v_exp_f32_e32 v0, v0
	v_add_f32_e32 v166, 1.0, v166
	v_add_f32_e32 v167, 1.0, v167
	v_min_f32_e32 v0, 0x7149f2ca, v0
	v_add_f32_e32 v0, 1.0, v0
	v_rcp_f32_e32 v169, v0
	v_lshlrev_b32_e32 v0, 16, v229
	v_mul_f32_e32 v0, 0xbfb8aa3b, v0
	v_exp_f32_e32 v0, v0
	v_mul_f32_e32 v166, v166, v168
	v_mul_f32_e32 v167, v167, v169
	v_min_f32_e32 v2, 0x7149f2ca, v0
	v_lshlrev_b32_e32 v0, 16, v225
	v_mul_f32_e32 v0, 0xbfb8aa3b, v0
	v_exp_f32_e32 v0, v0
	v_mul_f32_e32 v36, v36, v166
	v_mul_f32_e32 v37, v37, v167
	v_min_f32_e32 v0, 0x7149f2ca, v0
	v_add_f32_e32 v0, 1.0, v0
	v_rcp_f32_e32 v146, v0
	v_and_b32_e32 v0, 0xffff0000, v229
	v_mul_f32_e32 v0, 0xbfb8aa3b, v0
	v_exp_f32_e32 v0, v0
	s_nop 0
	v_min_f32_e32 v3, 0x7149f2ca, v0
	v_and_b32_e32 v0, 0xffff0000, v225
	v_mul_f32_e32 v0, 0xbfb8aa3b, v0
	v_exp_f32_e32 v0, v0
	v_add_f32_e32 v2, 1.0, v2
	v_add_f32_e32 v3, 1.0, v3
	v_min_f32_e32 v0, 0x7149f2ca, v0
	v_add_f32_e32 v0, 1.0, v0
	v_rcp_f32_e32 v147, v0
	v_mov_b32_e32 v0, v157
	v_mul_f32_e32 v2, v2, v146
	v_mul_f32_e32 v3, v3, v147
	s_nop 0
	v_mul_f32_e32 v38, v38, v2
	v_mul_f32_e32 v39, v39, v3
	s_nop 0
	s_nop 0
	v_mad_u64_u32 v[2:3], s[28:29], v0, s30, v[136:137]
	v_mov_b32_e32 v231, 0
	v_bfe_u32 v232, v186, 4, 1
	v_mul_u32_u24_e32 v232, 0x131fc, v232
	v_add_u32_e32 v2, v2, v232
	v_add_u32_e32 v230, s13, v2
	v_lshlrev_b64 v[232:233], 1, v[230:231]
	v_lshl_add_u64 v[198:199], s[4:5], 0, v[232:233]
	v_lshl_add_u64 v[202:203], s[8:9], 0, v[232:233]
	global_load_dwordx4 v[198:201], v[198:199], off
	global_load_dwordx4 v[202:205], v[202:203], off
	v_add_u32_e32 v230, s56, v2
	v_lshlrev_b64 v[232:233], 1, v[230:231]
	v_lshl_add_u64 v[206:207], s[4:5], 0, v[232:233]
	v_lshl_add_u64 v[210:211], s[8:9], 0, v[232:233]
	global_load_dwordx4 v[206:209], v[206:207], off
	global_load_dwordx4 v[210:213], v[210:211], off
	v_add_u32_e32 v230, s57, v2
	v_lshlrev_b64 v[232:233], 1, v[230:231]
	v_lshl_add_u64 v[214:215], s[4:5], 0, v[232:233]
	v_lshl_add_u64 v[218:219], s[8:9], 0, v[232:233]
	global_load_dwordx4 v[214:217], v[214:215], off
	global_load_dwordx4 v[218:221], v[218:219], off
	v_add_u32_e32 v230, s58, v2
	v_lshlrev_b64 v[232:233], 1, v[230:231]
	v_lshl_add_u64 v[222:223], s[4:5], 0, v[232:233]
	v_lshl_add_u64 v[226:227], s[8:9], 0, v[232:233]
	global_load_dwordx4 v[222:225], v[222:223], off
	global_load_dwordx4 v[226:229], v[226:227], off
	s_waitcnt vmcnt(6)
	v_permlane16_swap_b32_e32 v198, v200
	v_permlane16_swap_b32_e32 v199, v201
	v_permlane16_swap_b32_e32 v202, v204
	v_permlane16_swap_b32_e32 v203, v205
	v_lshlrev_b32_e32 v0, 16, v202
	v_mul_f32_e32 v0, 0xbfb8aa3b, v0
	v_exp_f32_e32 v0, v0
	s_nop 0
	v_min_f32_e32 v168, 0x7149f2ca, v0
	v_lshlrev_b32_e32 v0, 16, v198
	v_mul_f32_e32 v0, 0xbfb8aa3b, v0
	v_exp_f32_e32 v0, v0
	s_nop 0
	v_min_f32_e32 v0, 0x7149f2ca, v0
	v_add_f32_e32 v0, 1.0, v0
	v_rcp_f32_e32 v170, v0
	v_and_b32_e32 v0, 0xffff0000, v202
	v_mul_f32_e32 v0, 0xbfb8aa3b, v0
	v_exp_f32_e32 v0, v0
	s_nop 0
	v_min_f32_e32 v169, 0x7149f2ca, v0
	v_and_b32_e32 v0, 0xffff0000, v198
	v_mul_f32_e32 v0, 0xbfb8aa3b, v0
	v_exp_f32_e32 v0, v0
	v_add_f32_e32 v168, 1.0, v168
	v_add_f32_e32 v169, 1.0, v169
	v_min_f32_e32 v0, 0x7149f2ca, v0
	v_add_f32_e32 v0, 1.0, v0
	v_rcp_f32_e32 v171, v0
	v_lshlrev_b32_e32 v0, 16, v203
	v_mul_f32_e32 v0, 0xbfb8aa3b, v0
	v_exp_f32_e32 v0, v0
	v_mul_f32_e32 v168, v168, v170
	v_mul_f32_e32 v169, v169, v171
	v_min_f32_e32 v146, 0x7149f2ca, v0
	v_lshlrev_b32_e32 v0, 16, v199
	v_mul_f32_e32 v0, 0xbfb8aa3b, v0
	v_exp_f32_e32 v0, v0
	v_mul_f32_e32 v32, v32, v168
	v_mul_f32_e32 v33, v33, v169
	v_min_f32_e32 v0, 0x7149f2ca, v0
	v_add_f32_e32 v0, 1.0, v0
	v_rcp_f32_e32 v166, v0
	v_and_b32_e32 v0, 0xffff0000, v203
	v_mul_f32_e32 v0, 0xbfb8aa3b, v0
	v_exp_f32_e32 v0, v0
	s_nop 0
	v_min_f32_e32 v147, 0x7149f2ca, v0
	v_and_b32_e32 v0, 0xffff0000, v199
	v_mul_f32_e32 v0, 0xbfb8aa3b, v0
	v_exp_f32_e32 v0, v0
	v_add_f32_e32 v146, 1.0, v146
	v_add_f32_e32 v147, 1.0, v147
	v_min_f32_e32 v0, 0x7149f2ca, v0
	v_add_f32_e32 v0, 1.0, v0
	v_rcp_f32_e32 v167, v0
	s_nop 0
	v_mul_f32_e32 v146, v146, v166
	v_mul_f32_e32 v147, v147, v167
	s_nop 0
	v_mul_f32_e32 v34, v34, v146
	v_mul_f32_e32 v35, v35, v147
	s_nop 0
	s_nop 0
	s_nop 0
	s_waitcnt vmcnt(4)
	v_permlane16_swap_b32_e32 v206, v208
	v_permlane16_swap_b32_e32 v207, v209
	v_permlane16_swap_b32_e32 v210, v212
	v_permlane16_swap_b32_e32 v211, v213
	v_lshlrev_b32_e32 v0, 16, v210
	v_mul_f32_e32 v0, 0xbfb8aa3b, v0
	v_exp_f32_e32 v0, v0
	s_nop 0
	v_min_f32_e32 v168, 0x7149f2ca, v0
	v_lshlrev_b32_e32 v0, 16, v206
	v_mul_f32_e32 v0, 0xbfb8aa3b, v0
	v_exp_f32_e32 v0, v0
	s_nop 0
	v_min_f32_e32 v0, 0x7149f2ca, v0
	v_add_f32_e32 v0, 1.0, v0
	v_rcp_f32_e32 v170, v0
	v_and_b32_e32 v0, 0xffff0000, v210
	v_mul_f32_e32 v0, 0xbfb8aa3b, v0
	v_exp_f32_e32 v0, v0
	s_nop 0
	v_min_f32_e32 v169, 0x7149f2ca, v0
	v_and_b32_e32 v0, 0xffff0000, v206
	v_mul_f32_e32 v0, 0xbfb8aa3b, v0
	v_exp_f32_e32 v0, v0
	v_add_f32_e32 v168, 1.0, v168
	v_add_f32_e32 v169, 1.0, v169
	v_min_f32_e32 v0, 0x7149f2ca, v0
	v_add_f32_e32 v0, 1.0, v0
	v_rcp_f32_e32 v171, v0
	v_lshlrev_b32_e32 v0, 16, v211
	v_mul_f32_e32 v0, 0xbfb8aa3b, v0
	v_exp_f32_e32 v0, v0
	v_mul_f32_e32 v168, v168, v170
	v_mul_f32_e32 v169, v169, v171
	v_min_f32_e32 v146, 0x7149f2ca, v0
	v_lshlrev_b32_e32 v0, 16, v207
	v_mul_f32_e32 v0, 0xbfb8aa3b, v0
	v_exp_f32_e32 v0, v0
	v_mul_f32_e32 v28, v28, v168
	v_mul_f32_e32 v29, v29, v169
	v_min_f32_e32 v0, 0x7149f2ca, v0
	v_add_f32_e32 v0, 1.0, v0
	v_rcp_f32_e32 v166, v0
	v_and_b32_e32 v0, 0xffff0000, v211
	v_mul_f32_e32 v0, 0xbfb8aa3b, v0
	v_exp_f32_e32 v0, v0
	s_nop 0
	v_min_f32_e32 v147, 0x7149f2ca, v0
	v_and_b32_e32 v0, 0xffff0000, v207
	v_mul_f32_e32 v0, 0xbfb8aa3b, v0
	v_exp_f32_e32 v0, v0
	v_add_f32_e32 v146, 1.0, v146
	v_add_f32_e32 v147, 1.0, v147
	v_min_f32_e32 v0, 0x7149f2ca, v0
	v_add_f32_e32 v0, 1.0, v0
	v_rcp_f32_e32 v167, v0
	s_nop 0
	v_mul_f32_e32 v146, v146, v166
	v_mul_f32_e32 v147, v147, v167
	s_nop 0
	v_mul_f32_e32 v30, v30, v146
	v_mul_f32_e32 v31, v31, v147
	s_nop 0
	s_nop 0
	s_nop 0
	s_waitcnt vmcnt(2)
	v_permlane16_swap_b32_e32 v214, v216
	v_permlane16_swap_b32_e32 v215, v217
	v_permlane16_swap_b32_e32 v218, v220
	v_permlane16_swap_b32_e32 v219, v221
	v_lshlrev_b32_e32 v0, 16, v218
	v_mul_f32_e32 v0, 0xbfb8aa3b, v0
	v_exp_f32_e32 v0, v0
	s_nop 0
	v_min_f32_e32 v168, 0x7149f2ca, v0
	v_lshlrev_b32_e32 v0, 16, v214
	v_mul_f32_e32 v0, 0xbfb8aa3b, v0
	v_exp_f32_e32 v0, v0
	s_nop 0
	v_min_f32_e32 v0, 0x7149f2ca, v0
	v_add_f32_e32 v0, 1.0, v0
	v_rcp_f32_e32 v170, v0
	v_and_b32_e32 v0, 0xffff0000, v218
	v_mul_f32_e32 v0, 0xbfb8aa3b, v0
	v_exp_f32_e32 v0, v0
	s_nop 0
	v_min_f32_e32 v169, 0x7149f2ca, v0
	v_and_b32_e32 v0, 0xffff0000, v214
	v_mul_f32_e32 v0, 0xbfb8aa3b, v0
	v_exp_f32_e32 v0, v0
	v_add_f32_e32 v168, 1.0, v168
	v_add_f32_e32 v169, 1.0, v169
	v_min_f32_e32 v0, 0x7149f2ca, v0
	v_add_f32_e32 v0, 1.0, v0
	v_rcp_f32_e32 v171, v0
	v_lshlrev_b32_e32 v0, 16, v219
	v_mul_f32_e32 v0, 0xbfb8aa3b, v0
	v_exp_f32_e32 v0, v0
	v_mul_f32_e32 v168, v168, v170
	v_mul_f32_e32 v169, v169, v171
	v_min_f32_e32 v146, 0x7149f2ca, v0
	v_lshlrev_b32_e32 v0, 16, v215
	v_mul_f32_e32 v0, 0xbfb8aa3b, v0
	v_exp_f32_e32 v0, v0
	v_mul_f32_e32 v24, v24, v168
	v_mul_f32_e32 v25, v25, v169
	v_min_f32_e32 v0, 0x7149f2ca, v0
	v_add_f32_e32 v0, 1.0, v0
	v_rcp_f32_e32 v166, v0
	v_and_b32_e32 v0, 0xffff0000, v219
	v_mul_f32_e32 v0, 0xbfb8aa3b, v0
	v_exp_f32_e32 v0, v0
	s_nop 0
	v_min_f32_e32 v147, 0x7149f2ca, v0
	v_and_b32_e32 v0, 0xffff0000, v215
	v_mul_f32_e32 v0, 0xbfb8aa3b, v0
	v_exp_f32_e32 v0, v0
	v_add_f32_e32 v146, 1.0, v146
	v_add_f32_e32 v147, 1.0, v147
	v_min_f32_e32 v0, 0x7149f2ca, v0
	v_add_f32_e32 v0, 1.0, v0
	v_rcp_f32_e32 v167, v0
	s_nop 0
	s_nop 0
	v_mul_f32_e32 v146, v146, v166
	v_mul_f32_e32 v147, v147, v167
	s_nop 0
	v_mul_f32_e32 v26, v26, v146
	v_mul_f32_e32 v27, v27, v147
	s_nop 0
	s_nop 0
	s_waitcnt vmcnt(0)
	v_permlane16_swap_b32_e32 v222, v224
	v_permlane16_swap_b32_e32 v223, v225
	v_permlane16_swap_b32_e32 v226, v228
	v_permlane16_swap_b32_e32 v227, v229
	v_lshlrev_b32_e32 v0, 16, v226
	v_mul_f32_e32 v0, 0xbfb8aa3b, v0
	v_exp_f32_e32 v0, v0
	s_nop 0
	v_min_f32_e32 v166, 0x7149f2ca, v0
	v_lshlrev_b32_e32 v0, 16, v222
	v_mul_f32_e32 v0, 0xbfb8aa3b, v0
	v_exp_f32_e32 v0, v0
	s_nop 0
	v_min_f32_e32 v0, 0x7149f2ca, v0
	v_add_f32_e32 v0, 1.0, v0
	v_rcp_f32_e32 v168, v0
	v_and_b32_e32 v0, 0xffff0000, v226
	v_mul_f32_e32 v0, 0xbfb8aa3b, v0
	v_exp_f32_e32 v0, v0
	s_nop 0
	v_min_f32_e32 v167, 0x7149f2ca, v0
	v_and_b32_e32 v0, 0xffff0000, v222
	v_mul_f32_e32 v0, 0xbfb8aa3b, v0
	v_exp_f32_e32 v0, v0
	v_add_f32_e32 v166, 1.0, v166
	v_add_f32_e32 v167, 1.0, v167
	v_min_f32_e32 v0, 0x7149f2ca, v0
	v_add_f32_e32 v0, 1.0, v0
	v_rcp_f32_e32 v169, v0
	v_lshlrev_b32_e32 v0, 16, v227
	v_mul_f32_e32 v0, 0xbfb8aa3b, v0
	v_exp_f32_e32 v0, v0
	v_mul_f32_e32 v166, v166, v168
	v_mul_f32_e32 v167, v167, v169
	v_min_f32_e32 v2, 0x7149f2ca, v0
	v_lshlrev_b32_e32 v0, 16, v223
	v_mul_f32_e32 v0, 0xbfb8aa3b, v0
	v_exp_f32_e32 v0, v0
	v_mul_f32_e32 v20, v20, v166
	v_mul_f32_e32 v21, v21, v167
	v_min_f32_e32 v0, 0x7149f2ca, v0
	v_add_f32_e32 v0, 1.0, v0
	v_rcp_f32_e32 v146, v0
	v_and_b32_e32 v0, 0xffff0000, v227
	v_mul_f32_e32 v0, 0xbfb8aa3b, v0
	v_exp_f32_e32 v0, v0
	s_nop 0
	v_min_f32_e32 v3, 0x7149f2ca, v0
	v_and_b32_e32 v0, 0xffff0000, v223
	v_mul_f32_e32 v0, 0xbfb8aa3b, v0
	v_exp_f32_e32 v0, v0
	v_add_f32_e32 v2, 1.0, v2
	v_add_f32_e32 v3, 1.0, v3
	v_min_f32_e32 v0, 0x7149f2ca, v0
	v_add_f32_e32 v0, 1.0, v0
	v_rcp_f32_e32 v147, v0
	v_mov_b32_e32 v0, v158
	v_mul_f32_e32 v2, v2, v146
	v_mul_f32_e32 v3, v3, v147
	s_nop 0
	v_mul_f32_e32 v22, v22, v2
	v_mul_f32_e32 v23, v23, v3
	s_nop 0
	s_nop 0
	v_mad_u64_u32 v[2:3], s[28:29], v0, s30, v[136:137]
	v_lshlrev_b32_e32 v0, 16, v204
	v_mul_f32_e32 v0, 0xbfb8aa3b, v0
	v_exp_f32_e32 v0, v0
	s_nop 0
	v_min_f32_e32 v168, 0x7149f2ca, v0
	v_lshlrev_b32_e32 v0, 16, v200
	v_mul_f32_e32 v0, 0xbfb8aa3b, v0
	v_exp_f32_e32 v0, v0
	s_nop 0
	v_min_f32_e32 v0, 0x7149f2ca, v0
	v_add_f32_e32 v0, 1.0, v0
	v_rcp_f32_e32 v170, v0
	v_and_b32_e32 v0, 0xffff0000, v204
	v_mul_f32_e32 v0, 0xbfb8aa3b, v0
	v_exp_f32_e32 v0, v0
	s_nop 0
	v_min_f32_e32 v169, 0x7149f2ca, v0
	v_and_b32_e32 v0, 0xffff0000, v200
	v_mul_f32_e32 v0, 0xbfb8aa3b, v0
	v_exp_f32_e32 v0, v0
	v_add_f32_e32 v168, 1.0, v168
	v_add_f32_e32 v169, 1.0, v169
	v_min_f32_e32 v0, 0x7149f2ca, v0
	v_add_f32_e32 v0, 1.0, v0
	v_rcp_f32_e32 v171, v0
	v_lshlrev_b32_e32 v0, 16, v205
	v_mul_f32_e32 v0, 0xbfb8aa3b, v0
	v_exp_f32_e32 v0, v0
	v_mul_f32_e32 v168, v168, v170
	v_mul_f32_e32 v169, v169, v171
	v_min_f32_e32 v146, 0x7149f2ca, v0
	v_lshlrev_b32_e32 v0, 16, v201
	v_mul_f32_e32 v0, 0xbfb8aa3b, v0
	v_exp_f32_e32 v0, v0
	v_mul_f32_e32 v16, v16, v168
	v_mul_f32_e32 v17, v17, v169
	v_min_f32_e32 v0, 0x7149f2ca, v0
	v_add_f32_e32 v0, 1.0, v0
	v_rcp_f32_e32 v166, v0
	v_and_b32_e32 v0, 0xffff0000, v205
	v_mul_f32_e32 v0, 0xbfb8aa3b, v0
	v_exp_f32_e32 v0, v0
	s_nop 0
	v_min_f32_e32 v147, 0x7149f2ca, v0
	v_and_b32_e32 v0, 0xffff0000, v201
	v_mul_f32_e32 v0, 0xbfb8aa3b, v0
	v_exp_f32_e32 v0, v0
	v_add_f32_e32 v146, 1.0, v146
	v_add_f32_e32 v147, 1.0, v147
	v_min_f32_e32 v0, 0x7149f2ca, v0
	v_add_f32_e32 v0, 1.0, v0
	v_rcp_f32_e32 v167, v0
	s_nop 0
	v_mul_f32_e32 v146, v146, v166
	v_mul_f32_e32 v147, v147, v167
	s_nop 0
	v_mul_f32_e32 v18, v18, v146
	v_mul_f32_e32 v19, v19, v147
	s_nop 0
	s_nop 0
	s_nop 0
	s_waitcnt vmcnt(4)
	v_lshlrev_b32_e32 v0, 16, v212
	v_mul_f32_e32 v0, 0xbfb8aa3b, v0
	v_exp_f32_e32 v0, v0
	s_nop 0
	v_min_f32_e32 v168, 0x7149f2ca, v0
	v_lshlrev_b32_e32 v0, 16, v208
	v_mul_f32_e32 v0, 0xbfb8aa3b, v0
	v_exp_f32_e32 v0, v0
	s_nop 0
	v_min_f32_e32 v0, 0x7149f2ca, v0
	v_add_f32_e32 v0, 1.0, v0
	v_rcp_f32_e32 v170, v0
	v_and_b32_e32 v0, 0xffff0000, v212
	v_mul_f32_e32 v0, 0xbfb8aa3b, v0
	v_exp_f32_e32 v0, v0
	s_nop 0
	v_min_f32_e32 v169, 0x7149f2ca, v0
	v_and_b32_e32 v0, 0xffff0000, v208
	v_mul_f32_e32 v0, 0xbfb8aa3b, v0
	v_exp_f32_e32 v0, v0
	v_add_f32_e32 v168, 1.0, v168
	v_add_f32_e32 v169, 1.0, v169
	v_min_f32_e32 v0, 0x7149f2ca, v0
	v_add_f32_e32 v0, 1.0, v0
	v_rcp_f32_e32 v171, v0
	v_lshlrev_b32_e32 v0, 16, v213
	v_mul_f32_e32 v0, 0xbfb8aa3b, v0
	v_exp_f32_e32 v0, v0
	v_mul_f32_e32 v168, v168, v170
	v_mul_f32_e32 v169, v169, v171
	v_min_f32_e32 v146, 0x7149f2ca, v0
	v_lshlrev_b32_e32 v0, 16, v209
	v_mul_f32_e32 v0, 0xbfb8aa3b, v0
	v_exp_f32_e32 v0, v0
	v_mul_f32_e32 v12, v12, v168
	v_mul_f32_e32 v13, v13, v169
	v_min_f32_e32 v0, 0x7149f2ca, v0
	v_add_f32_e32 v0, 1.0, v0
	v_rcp_f32_e32 v166, v0
	v_and_b32_e32 v0, 0xffff0000, v213
	v_mul_f32_e32 v0, 0xbfb8aa3b, v0
	v_exp_f32_e32 v0, v0
	s_nop 0
	v_min_f32_e32 v147, 0x7149f2ca, v0
	v_and_b32_e32 v0, 0xffff0000, v209
	v_mul_f32_e32 v0, 0xbfb8aa3b, v0
	v_exp_f32_e32 v0, v0
	v_add_f32_e32 v146, 1.0, v146
	v_add_f32_e32 v147, 1.0, v147
	v_min_f32_e32 v0, 0x7149f2ca, v0
	v_add_f32_e32 v0, 1.0, v0
	v_rcp_f32_e32 v167, v0
	s_nop 0
	v_mul_f32_e32 v146, v146, v166
	v_mul_f32_e32 v147, v147, v167
	s_nop 0
	v_mul_f32_e32 v14, v14, v146
	v_mul_f32_e32 v15, v15, v147
	s_nop 0
	s_nop 0
	s_nop 0
	s_waitcnt vmcnt(2)
	v_lshlrev_b32_e32 v0, 16, v220
	v_mul_f32_e32 v0, 0xbfb8aa3b, v0
	v_exp_f32_e32 v0, v0
	s_nop 0
	v_min_f32_e32 v168, 0x7149f2ca, v0
	v_lshlrev_b32_e32 v0, 16, v216
	v_mul_f32_e32 v0, 0xbfb8aa3b, v0
	v_exp_f32_e32 v0, v0
	s_nop 0
	v_min_f32_e32 v0, 0x7149f2ca, v0
	v_add_f32_e32 v0, 1.0, v0
	v_rcp_f32_e32 v170, v0
	v_and_b32_e32 v0, 0xffff0000, v220
	v_mul_f32_e32 v0, 0xbfb8aa3b, v0
	v_exp_f32_e32 v0, v0
	s_nop 0
	v_min_f32_e32 v169, 0x7149f2ca, v0
	v_and_b32_e32 v0, 0xffff0000, v216
	v_mul_f32_e32 v0, 0xbfb8aa3b, v0
	v_exp_f32_e32 v0, v0
	v_add_f32_e32 v168, 1.0, v168
	v_add_f32_e32 v169, 1.0, v169
	v_min_f32_e32 v0, 0x7149f2ca, v0
	v_add_f32_e32 v0, 1.0, v0
	v_rcp_f32_e32 v171, v0
	v_lshlrev_b32_e32 v0, 16, v221
	v_mul_f32_e32 v0, 0xbfb8aa3b, v0
	v_exp_f32_e32 v0, v0
	v_mul_f32_e32 v168, v168, v170
	v_mul_f32_e32 v169, v169, v171
	v_min_f32_e32 v146, 0x7149f2ca, v0
	v_lshlrev_b32_e32 v0, 16, v217
	v_mul_f32_e32 v0, 0xbfb8aa3b, v0
	v_exp_f32_e32 v0, v0
	v_mul_f32_e32 v8, v8, v168
	v_mul_f32_e32 v9, v9, v169
	v_min_f32_e32 v0, 0x7149f2ca, v0
	v_add_f32_e32 v0, 1.0, v0
	v_rcp_f32_e32 v166, v0
	v_and_b32_e32 v0, 0xffff0000, v221
	v_mul_f32_e32 v0, 0xbfb8aa3b, v0
	v_exp_f32_e32 v0, v0
	s_nop 0
	v_min_f32_e32 v147, 0x7149f2ca, v0
	v_and_b32_e32 v0, 0xffff0000, v217
	v_mul_f32_e32 v0, 0xbfb8aa3b, v0
	v_exp_f32_e32 v0, v0
	v_add_f32_e32 v146, 1.0, v146
	v_add_f32_e32 v147, 1.0, v147
	v_min_f32_e32 v0, 0x7149f2ca, v0
	v_add_f32_e32 v0, 1.0, v0
	v_rcp_f32_e32 v167, v0
	s_nop 0
	v_mul_f32_e32 v146, v146, v166
	v_mul_f32_e32 v147, v147, v167
	s_nop 0
	v_mul_f32_e32 v10, v10, v146
	v_mul_f32_e32 v11, v11, v147
	s_nop 0
	s_nop 0
	s_nop 0
	s_waitcnt vmcnt(0)
	v_lshlrev_b32_e32 v0, 16, v228
	v_mul_f32_e32 v0, 0xbfb8aa3b, v0
	v_exp_f32_e32 v0, v0
	s_nop 0
	v_min_f32_e32 v146, 0x7149f2ca, v0
	v_lshlrev_b32_e32 v0, 16, v224
	v_mul_f32_e32 v0, 0xbfb8aa3b, v0
	v_exp_f32_e32 v0, v0
	s_nop 0
	v_min_f32_e32 v0, 0x7149f2ca, v0
	v_add_f32_e32 v0, 1.0, v0
	v_rcp_f32_e32 v168, v0
	v_and_b32_e32 v0, 0xffff0000, v228
	v_mul_f32_e32 v0, 0xbfb8aa3b, v0
	v_exp_f32_e32 v0, v0
	s_nop 0
	v_min_f32_e32 v147, 0x7149f2ca, v0
	v_and_b32_e32 v0, 0xffff0000, v224
	v_mul_f32_e32 v0, 0xbfb8aa3b, v0
	v_exp_f32_e32 v0, v0
	v_add_f32_e32 v146, 1.0, v146
	v_add_f32_e32 v147, 1.0, v147
	v_min_f32_e32 v0, 0x7149f2ca, v0
	v_add_f32_e32 v0, 1.0, v0
	v_rcp_f32_e32 v169, v0
	v_lshlrev_b32_e32 v0, 16, v229
	v_mul_f32_e32 v0, 0xbfb8aa3b, v0
	v_exp_f32_e32 v0, v0
	v_mul_f32_e32 v146, v146, v168
	v_mul_f32_e32 v147, v147, v169
	v_min_f32_e32 v166, 0x7149f2ca, v0
	v_lshlrev_b32_e32 v0, 16, v225
	v_mul_f32_e32 v0, 0xbfb8aa3b, v0
	v_exp_f32_e32 v0, v0
	v_mul_f32_e32 v4, v4, v146
	v_mul_f32_e32 v5, v5, v147
	v_min_f32_e32 v0, 0x7149f2ca, v0
	v_add_f32_e32 v0, 1.0, v0
	v_rcp_f32_e32 v2, v0
	v_and_b32_e32 v0, 0xffff0000, v229
	v_mul_f32_e32 v0, 0xbfb8aa3b, v0
	v_exp_f32_e32 v0, v0
	s_nop 0
	v_min_f32_e32 v167, 0x7149f2ca, v0
	v_and_b32_e32 v0, 0xffff0000, v225
	v_mul_f32_e32 v0, 0xbfb8aa3b, v0
	v_exp_f32_e32 v0, v0
	v_add_f32_e32 v166, 1.0, v166
	v_add_f32_e32 v167, 1.0, v167
	v_min_f32_e32 v0, 0x7149f2ca, v0
	v_add_f32_e32 v0, 1.0, v0
	v_rcp_f32_e32 v3, v0
	s_nop 0
	v_mul_f32_e32 v2, v166, v2
	v_mul_f32_e32 v3, v167, v3
	s_nop 0
	v_mul_f32_e32 v6, v6, v2
	v_mul_f32_e32 v7, v7, v3
	s_nop 0
